# hand-written LN_in (one row per wave, loads three rows ahead) with nt row loads, on top of the nt streaming-load version
# speedup vs baseline: 1.0188x; 1.0020x over previous
.LBB0_70:
	s_or_b64 exec, exec, s[0:1]
	v_readlane_b32 s0, v240, 26
	s_waitcnt lgkmcnt(0)
	s_lshl_b32 s10, s96, 4
	v_readlane_b32 s1, v240, 27
	s_cmp_gt_i32 s0, 0x800f
	s_mov_b32 s15, 0
	v_cmp_eq_u32_e64 s[0:1], 0, v160
	s_cbranch_scc1 .LBB0_79
	v_readlane_b32 s4, v240, 26
	v_readlane_b32 s5, v240, 28
	s_ashr_i32 s6, s4, 31
	v_writelane_b32 v240, s6, 27
	v_readlane_b32 s40, v240, 8
	v_readlane_b32 s41, v240, 9
	v_readlane_b32 s42, v240, 10
	v_readlane_b32 s43, v240, 11
	v_lshlrev_b32_e32 v100, 4, v160
	v_lshlrev_b32_e32 v101, 3, v160
	v_mov_b32_e32 v109, 0
	v_mov_b32_e32 v108, 0x358637bd
	s_mov_b32 s37, 0x3a800000
	global_load_dwordx4 v[66:69], v100, s[40:41]
	global_load_dwordx4 v[82:85], v100, s[42:43]
	global_load_dwordx4 v[70:73], v100, s[40:41] offset:1024
	global_load_dwordx4 v[86:89], v100, s[42:43] offset:1024
	global_load_dwordx4 v[74:77], v100, s[40:41] offset:2048
	global_load_dwordx4 v[90:93], v100, s[42:43] offset:2048
	global_load_dwordx4 v[78:81], v100, s[40:41] offset:3072
	global_load_dwordx4 v[94:97], v100, s[42:43] offset:3072
	v_readlane_b32 s6, v240, 4
	v_readlane_b32 s7, v240, 5
	s_lshl_b32 s34, s5, 12
	s_lshl_b32 s35, s5, 11
	s_lshl_b32 s36, s5, 3
	s_lshl_b32 s38, s4, 12
	s_add_u32 s28, s6, s38
	s_addc_u32 s29, s7, 0
	s_lshl_b32 s38, s4, 11
	s_add_u32 s38, s38, 0x2400000
	s_add_u32 s30, s94, s38
	s_addc_u32 s31, s95, 0
	s_lshl_b32 s38, s4, 3
	s_add_u32 s32, s94, s38
	s_addc_u32 s33, s95, 0
	s_waitcnt vmcnt(0)
	global_load_dwordx4 v[2:5], v100, s[28:29] nt
	global_load_dwordx4 v[6:9], v100, s[28:29] offset:1024 nt
	global_load_dwordx4 v[10:13], v100, s[28:29] offset:2048 nt
	global_load_dwordx4 v[14:17], v100, s[28:29] offset:3072 nt
	s_add_u32 s28, s28, s34
	s_addc_u32 s29, s29, 0
	global_load_dwordx4 v[18:21], v100, s[28:29] nt
	global_load_dwordx4 v[22:25], v100, s[28:29] offset:1024 nt
	global_load_dwordx4 v[26:29], v100, s[28:29] offset:2048 nt
	global_load_dwordx4 v[30:33], v100, s[28:29] offset:3072 nt
	s_add_u32 s28, s28, s34
	s_addc_u32 s29, s29, 0
	global_load_dwordx4 v[34:37], v100, s[28:29] nt
	global_load_dwordx4 v[38:41], v100, s[28:29] offset:1024 nt
	global_load_dwordx4 v[42:45], v100, s[28:29] offset:2048 nt
	global_load_dwordx4 v[46:49], v100, s[28:29] offset:3072 nt
	s_add_u32 s28, s28, s34
	s_addc_u32 s29, s29, 0
	s_waitcnt vmcnt(8)
	global_load_dwordx4 v[50:53], v100, s[28:29] nt
	global_load_dwordx4 v[54:57], v100, s[28:29] offset:1024 nt
	global_load_dwordx4 v[58:61], v100, s[28:29] offset:2048 nt
	global_load_dwordx4 v[62:65], v100, s[28:29] offset:3072 nt
	s_add_u32 s28, s28, s34
	s_addc_u32 s29, s29, 0
	v_add_f32_e32 v104, v2, v3
	v_add_f32_e32 v105, v4, v5
	v_add_f32_e32 v104, v104, v105
	v_mov_b32_e32 v102, v104
	v_add_f32_e32 v104, v6, v7
	v_add_f32_e32 v105, v8, v9
	v_add_f32_e32 v104, v104, v105
	v_add_f32_e32 v102, v102, v104
	v_add_f32_e32 v104, v10, v11
	v_add_f32_e32 v105, v12, v13
	v_add_f32_e32 v104, v104, v105
	v_add_f32_e32 v102, v102, v104
	v_add_f32_e32 v104, v14, v15
	v_add_f32_e32 v105, v16, v17
	v_add_f32_e32 v104, v104, v105
	v_add_f32_e32 v102, v102, v104
	s_nop 1
	v_add_f32_dpp v102, v102, v102 quad_perm:[1,0,3,2] row_mask:0xf bank_mask:0xf
	s_nop 1
	v_add_f32_dpp v102, v102, v102 quad_perm:[2,3,0,1] row_mask:0xf bank_mask:0xf
	s_nop 1
	v_add_f32_dpp v102, v102, v102 row_half_mirror row_mask:0xf bank_mask:0xf
	s_nop 1
	v_add_f32_dpp v102, v102, v102 row_mirror row_mask:0xf bank_mask:0xf
	v_mov_b32_e32 v104, v102
	s_nop 1
	v_permlane16_swap_b32_e32 v102, v104
	s_nop 0
	v_add_f32_e32 v102, v102, v104
	v_mov_b32_e32 v104, v102
	s_nop 1
	v_permlane32_swap_b32_e32 v102, v104
	s_nop 0
	v_add_f32_e32 v102, v102, v104
	v_mul_f32_e32 v106, 0x3a800000, v102
	v_sub_f32_e32 v2, v2, v106
	v_sub_f32_e32 v3, v3, v106
	v_sub_f32_e32 v4, v4, v106
	v_sub_f32_e32 v5, v5, v106
	v_sub_f32_e32 v6, v6, v106
	v_sub_f32_e32 v7, v7, v106
	v_sub_f32_e32 v8, v8, v106
	v_sub_f32_e32 v9, v9, v106
	v_sub_f32_e32 v10, v10, v106
	v_sub_f32_e32 v11, v11, v106
	v_sub_f32_e32 v12, v12, v106
	v_sub_f32_e32 v13, v13, v106
	v_sub_f32_e32 v14, v14, v106
	v_sub_f32_e32 v15, v15, v106
	v_sub_f32_e32 v16, v16, v106
	v_sub_f32_e32 v17, v17, v106
	v_mul_f32_e32 v104, v2, v2
	v_mul_f32_e32 v105, v4, v4
	v_fmac_f32_e32 v104, v3, v3
	v_fmac_f32_e32 v105, v5, v5
	v_add_f32_e32 v104, v104, v105
	v_mov_b32_e32 v103, v104
	v_mul_f32_e32 v104, v6, v6
	v_mul_f32_e32 v105, v8, v8
	v_fmac_f32_e32 v104, v7, v7
	v_fmac_f32_e32 v105, v9, v9
	v_add_f32_e32 v104, v104, v105
	v_add_f32_e32 v103, v103, v104
	v_mul_f32_e32 v104, v10, v10
	v_mul_f32_e32 v105, v12, v12
	v_fmac_f32_e32 v104, v11, v11
	v_fmac_f32_e32 v105, v13, v13
	v_add_f32_e32 v104, v104, v105
	v_add_f32_e32 v103, v103, v104
	v_mul_f32_e32 v104, v14, v14
	v_mul_f32_e32 v105, v16, v16
	v_fmac_f32_e32 v104, v15, v15
	v_fmac_f32_e32 v105, v17, v17
	v_add_f32_e32 v104, v104, v105
	v_add_f32_e32 v103, v103, v104
	s_nop 1
	v_add_f32_dpp v103, v103, v103 quad_perm:[1,0,3,2] row_mask:0xf bank_mask:0xf
	s_nop 1
	v_add_f32_dpp v103, v103, v103 quad_perm:[2,3,0,1] row_mask:0xf bank_mask:0xf
	s_nop 1
	v_add_f32_dpp v103, v103, v103 row_half_mirror row_mask:0xf bank_mask:0xf
	s_nop 1
	v_add_f32_dpp v103, v103, v103 row_mirror row_mask:0xf bank_mask:0xf
	v_mov_b32_e32 v104, v103
	s_nop 1
	v_permlane16_swap_b32_e32 v103, v104
	s_nop 0
	v_add_f32_e32 v103, v103, v104
	v_mov_b32_e32 v104, v103
	s_nop 1
	v_permlane32_swap_b32_e32 v103, v104
	s_nop 0
	v_add_f32_e32 v103, v103, v104
	v_fma_f32 v103, v103, s37, v108
	v_rsq_f32_e32 v107, v103
	s_nop 0
	v_mul_f32_e32 v2, v2, v107
	v_mul_f32_e32 v3, v3, v107
	v_mul_f32_e32 v4, v4, v107
	v_mul_f32_e32 v5, v5, v107
	v_mul_f32_e32 v6, v6, v107
	v_mul_f32_e32 v7, v7, v107
	v_mul_f32_e32 v8, v8, v107
	v_mul_f32_e32 v9, v9, v107
	v_mul_f32_e32 v10, v10, v107
	v_mul_f32_e32 v11, v11, v107
	v_mul_f32_e32 v12, v12, v107
	v_mul_f32_e32 v13, v13, v107
	v_mul_f32_e32 v14, v14, v107
	v_mul_f32_e32 v15, v15, v107
	v_mul_f32_e32 v16, v16, v107
	v_mul_f32_e32 v17, v17, v107
	v_fma_f32 v2, v2, v66, v82
	v_fma_f32 v3, v3, v67, v83
	v_fma_f32 v4, v4, v68, v84
	v_fma_f32 v5, v5, v69, v85
	v_fma_f32 v6, v6, v70, v86
	v_fma_f32 v7, v7, v71, v87
	v_fma_f32 v8, v8, v72, v88
	v_fma_f32 v9, v9, v73, v89
	v_fma_f32 v10, v10, v74, v90
	v_fma_f32 v11, v11, v75, v91
	v_fma_f32 v12, v12, v76, v92
	v_fma_f32 v13, v13, v77, v93
	v_fma_f32 v14, v14, v78, v94
	v_fma_f32 v15, v15, v79, v95
	v_fma_f32 v16, v16, v80, v96
	v_fma_f32 v17, v17, v81, v97
	v_cvt_pk_bf16_f32 v110, v2, v3
	v_cvt_pk_bf16_f32 v111, v4, v5
	v_cvt_pk_bf16_f32 v112, v6, v7
	v_cvt_pk_bf16_f32 v113, v8, v9
	v_cvt_pk_bf16_f32 v114, v10, v11
	v_cvt_pk_bf16_f32 v115, v12, v13
	v_cvt_pk_bf16_f32 v116, v14, v15
	v_cvt_pk_bf16_f32 v117, v16, v17
	global_store_dwordx2 v101, v[110:111], s[30:31]
	global_store_dwordx2 v101, v[112:113], s[30:31] offset:512
	global_store_dwordx2 v101, v[114:115], s[30:31] offset:1024
	global_store_dwordx2 v101, v[116:117], s[30:31] offset:1536
	s_mov_b64 exec, s[0:1]
	global_store_dwordx2 v109, v[106:107], s[32:33]
	s_mov_b64 exec, -1
	s_add_u32 s30, s30, s35
	s_addc_u32 s31, s31, 0
	s_add_u32 s32, s32, s36
	s_addc_u32 s33, s33, 0
	s_waitcnt vmcnt(13)
	global_load_dwordx4 v[2:5], v100, s[28:29] nt
	global_load_dwordx4 v[6:9], v100, s[28:29] offset:1024 nt
	global_load_dwordx4 v[10:13], v100, s[28:29] offset:2048 nt
	global_load_dwordx4 v[14:17], v100, s[28:29] offset:3072 nt
	s_add_u32 s28, s28, s34
	s_addc_u32 s29, s29, 0
	v_add_f32_e32 v104, v18, v19
	v_add_f32_e32 v105, v20, v21
	v_add_f32_e32 v104, v104, v105
	v_mov_b32_e32 v102, v104
	v_add_f32_e32 v104, v22, v23
	v_add_f32_e32 v105, v24, v25
	v_add_f32_e32 v104, v104, v105
	v_add_f32_e32 v102, v102, v104
	v_add_f32_e32 v104, v26, v27
	v_add_f32_e32 v105, v28, v29
	v_add_f32_e32 v104, v104, v105
	v_add_f32_e32 v102, v102, v104
	v_add_f32_e32 v104, v30, v31
	v_add_f32_e32 v105, v32, v33
	v_add_f32_e32 v104, v104, v105
	v_add_f32_e32 v102, v102, v104
	s_nop 1
	v_add_f32_dpp v102, v102, v102 quad_perm:[1,0,3,2] row_mask:0xf bank_mask:0xf
	s_nop 1
	v_add_f32_dpp v102, v102, v102 quad_perm:[2,3,0,1] row_mask:0xf bank_mask:0xf
	s_nop 1
	v_add_f32_dpp v102, v102, v102 row_half_mirror row_mask:0xf bank_mask:0xf
	s_nop 1
	v_add_f32_dpp v102, v102, v102 row_mirror row_mask:0xf bank_mask:0xf
	v_mov_b32_e32 v104, v102
	s_nop 1
	v_permlane16_swap_b32_e32 v102, v104
	s_nop 0
	v_add_f32_e32 v102, v102, v104
	v_mov_b32_e32 v104, v102
	s_nop 1
	v_permlane32_swap_b32_e32 v102, v104
	s_nop 0
	v_add_f32_e32 v102, v102, v104
	v_mul_f32_e32 v106, 0x3a800000, v102
	v_sub_f32_e32 v18, v18, v106
	v_sub_f32_e32 v19, v19, v106
	v_sub_f32_e32 v20, v20, v106
	v_sub_f32_e32 v21, v21, v106
	v_sub_f32_e32 v22, v22, v106
	v_sub_f32_e32 v23, v23, v106
	v_sub_f32_e32 v24, v24, v106
	v_sub_f32_e32 v25, v25, v106
	v_sub_f32_e32 v26, v26, v106
	v_sub_f32_e32 v27, v27, v106
	v_sub_f32_e32 v28, v28, v106
	v_sub_f32_e32 v29, v29, v106
	v_sub_f32_e32 v30, v30, v106
	v_sub_f32_e32 v31, v31, v106
	v_sub_f32_e32 v32, v32, v106
	v_sub_f32_e32 v33, v33, v106
	v_mul_f32_e32 v104, v18, v18
	v_mul_f32_e32 v105, v20, v20
	v_fmac_f32_e32 v104, v19, v19
	v_fmac_f32_e32 v105, v21, v21
	v_add_f32_e32 v104, v104, v105
	v_mov_b32_e32 v103, v104
	v_mul_f32_e32 v104, v22, v22
	v_mul_f32_e32 v105, v24, v24
	v_fmac_f32_e32 v104, v23, v23
	v_fmac_f32_e32 v105, v25, v25
	v_add_f32_e32 v104, v104, v105
	v_add_f32_e32 v103, v103, v104
	v_mul_f32_e32 v104, v26, v26
	v_mul_f32_e32 v105, v28, v28
	v_fmac_f32_e32 v104, v27, v27
	v_fmac_f32_e32 v105, v29, v29
	v_add_f32_e32 v104, v104, v105
	v_add_f32_e32 v103, v103, v104
	v_mul_f32_e32 v104, v30, v30
	v_mul_f32_e32 v105, v32, v32
	v_fmac_f32_e32 v104, v31, v31
	v_fmac_f32_e32 v105, v33, v33
	v_add_f32_e32 v104, v104, v105
	v_add_f32_e32 v103, v103, v104
	s_nop 1
	v_add_f32_dpp v103, v103, v103 quad_perm:[1,0,3,2] row_mask:0xf bank_mask:0xf
	s_nop 1
	v_add_f32_dpp v103, v103, v103 quad_perm:[2,3,0,1] row_mask:0xf bank_mask:0xf
	s_nop 1
	v_add_f32_dpp v103, v103, v103 row_half_mirror row_mask:0xf bank_mask:0xf
	s_nop 1
	v_add_f32_dpp v103, v103, v103 row_mirror row_mask:0xf bank_mask:0xf
	v_mov_b32_e32 v104, v103
	s_nop 1
	v_permlane16_swap_b32_e32 v103, v104
	s_nop 0
	v_add_f32_e32 v103, v103, v104
	v_mov_b32_e32 v104, v103
	s_nop 1
	v_permlane32_swap_b32_e32 v103, v104
	s_nop 0
	v_add_f32_e32 v103, v103, v104
	v_fma_f32 v103, v103, s37, v108
	v_rsq_f32_e32 v107, v103
	s_nop 0
	v_mul_f32_e32 v18, v18, v107
	v_mul_f32_e32 v19, v19, v107
	v_mul_f32_e32 v20, v20, v107
	v_mul_f32_e32 v21, v21, v107
	v_mul_f32_e32 v22, v22, v107
	v_mul_f32_e32 v23, v23, v107
	v_mul_f32_e32 v24, v24, v107
	v_mul_f32_e32 v25, v25, v107
	v_mul_f32_e32 v26, v26, v107
	v_mul_f32_e32 v27, v27, v107
	v_mul_f32_e32 v28, v28, v107
	v_mul_f32_e32 v29, v29, v107
	v_mul_f32_e32 v30, v30, v107
	v_mul_f32_e32 v31, v31, v107
	v_mul_f32_e32 v32, v32, v107
	v_mul_f32_e32 v33, v33, v107
	v_fma_f32 v18, v18, v66, v82
	v_fma_f32 v19, v19, v67, v83
	v_fma_f32 v20, v20, v68, v84
	v_fma_f32 v21, v21, v69, v85
	v_fma_f32 v22, v22, v70, v86
	v_fma_f32 v23, v23, v71, v87
	v_fma_f32 v24, v24, v72, v88
	v_fma_f32 v25, v25, v73, v89
	v_fma_f32 v26, v26, v74, v90
	v_fma_f32 v27, v27, v75, v91
	v_fma_f32 v28, v28, v76, v92
	v_fma_f32 v29, v29, v77, v93
	v_fma_f32 v30, v30, v78, v94
	v_fma_f32 v31, v31, v79, v95
	v_fma_f32 v32, v32, v80, v96
	v_fma_f32 v33, v33, v81, v97
	v_cvt_pk_bf16_f32 v110, v18, v19
	v_cvt_pk_bf16_f32 v111, v20, v21
	v_cvt_pk_bf16_f32 v112, v22, v23
	v_cvt_pk_bf16_f32 v113, v24, v25
	v_cvt_pk_bf16_f32 v114, v26, v27
	v_cvt_pk_bf16_f32 v115, v28, v29
	v_cvt_pk_bf16_f32 v116, v30, v31
	v_cvt_pk_bf16_f32 v117, v32, v33
	global_store_dwordx2 v101, v[110:111], s[30:31]
	global_store_dwordx2 v101, v[112:113], s[30:31] offset:512
	global_store_dwordx2 v101, v[114:115], s[30:31] offset:1024
	global_store_dwordx2 v101, v[116:117], s[30:31] offset:1536
	s_mov_b64 exec, s[0:1]
	global_store_dwordx2 v109, v[106:107], s[32:33]
	s_mov_b64 exec, -1
	s_add_u32 s30, s30, s35
	s_addc_u32 s31, s31, 0
	s_add_u32 s32, s32, s36
	s_addc_u32 s33, s33, 0
	s_waitcnt vmcnt(18)
	global_load_dwordx4 v[18:21], v100, s[28:29] nt
	global_load_dwordx4 v[22:25], v100, s[28:29] offset:1024 nt
	global_load_dwordx4 v[26:29], v100, s[28:29] offset:2048 nt
	global_load_dwordx4 v[30:33], v100, s[28:29] offset:3072 nt
	s_add_u32 s28, s28, s34
	s_addc_u32 s29, s29, 0
	v_add_f32_e32 v104, v34, v35
	v_add_f32_e32 v105, v36, v37
	v_add_f32_e32 v104, v104, v105
	v_mov_b32_e32 v102, v104
	v_add_f32_e32 v104, v38, v39
	v_add_f32_e32 v105, v40, v41
	v_add_f32_e32 v104, v104, v105
	v_add_f32_e32 v102, v102, v104
	v_add_f32_e32 v104, v42, v43
	v_add_f32_e32 v105, v44, v45
	v_add_f32_e32 v104, v104, v105
	v_add_f32_e32 v102, v102, v104
	v_add_f32_e32 v104, v46, v47
	v_add_f32_e32 v105, v48, v49
	v_add_f32_e32 v104, v104, v105
	v_add_f32_e32 v102, v102, v104
	s_nop 1
	v_add_f32_dpp v102, v102, v102 quad_perm:[1,0,3,2] row_mask:0xf bank_mask:0xf
	s_nop 1
	v_add_f32_dpp v102, v102, v102 quad_perm:[2,3,0,1] row_mask:0xf bank_mask:0xf
	s_nop 1
	v_add_f32_dpp v102, v102, v102 row_half_mirror row_mask:0xf bank_mask:0xf
	s_nop 1
	v_add_f32_dpp v102, v102, v102 row_mirror row_mask:0xf bank_mask:0xf
	v_mov_b32_e32 v104, v102
	s_nop 1
	v_permlane16_swap_b32_e32 v102, v104
	s_nop 0
	v_add_f32_e32 v102, v102, v104
	v_mov_b32_e32 v104, v102
	s_nop 1
	v_permlane32_swap_b32_e32 v102, v104
	s_nop 0
	v_add_f32_e32 v102, v102, v104
	v_mul_f32_e32 v106, 0x3a800000, v102
	v_sub_f32_e32 v34, v34, v106
	v_sub_f32_e32 v35, v35, v106
	v_sub_f32_e32 v36, v36, v106
	v_sub_f32_e32 v37, v37, v106
	v_sub_f32_e32 v38, v38, v106
	v_sub_f32_e32 v39, v39, v106
	v_sub_f32_e32 v40, v40, v106
	v_sub_f32_e32 v41, v41, v106
	v_sub_f32_e32 v42, v42, v106
	v_sub_f32_e32 v43, v43, v106
	v_sub_f32_e32 v44, v44, v106
	v_sub_f32_e32 v45, v45, v106
	v_sub_f32_e32 v46, v46, v106
	v_sub_f32_e32 v47, v47, v106
	v_sub_f32_e32 v48, v48, v106
	v_sub_f32_e32 v49, v49, v106
	v_mul_f32_e32 v104, v34, v34
	v_mul_f32_e32 v105, v36, v36
	v_fmac_f32_e32 v104, v35, v35
	v_fmac_f32_e32 v105, v37, v37
	v_add_f32_e32 v104, v104, v105
	v_mov_b32_e32 v103, v104
	v_mul_f32_e32 v104, v38, v38
	v_mul_f32_e32 v105, v40, v40
	v_fmac_f32_e32 v104, v39, v39
	v_fmac_f32_e32 v105, v41, v41
	v_add_f32_e32 v104, v104, v105
	v_add_f32_e32 v103, v103, v104
	v_mul_f32_e32 v104, v42, v42
	v_mul_f32_e32 v105, v44, v44
	v_fmac_f32_e32 v104, v43, v43
	v_fmac_f32_e32 v105, v45, v45
	v_add_f32_e32 v104, v104, v105
	v_add_f32_e32 v103, v103, v104
	v_mul_f32_e32 v104, v46, v46
	v_mul_f32_e32 v105, v48, v48
	v_fmac_f32_e32 v104, v47, v47
	v_fmac_f32_e32 v105, v49, v49
	v_add_f32_e32 v104, v104, v105
	v_add_f32_e32 v103, v103, v104
	s_nop 1
	v_add_f32_dpp v103, v103, v103 quad_perm:[1,0,3,2] row_mask:0xf bank_mask:0xf
	s_nop 1
	v_add_f32_dpp v103, v103, v103 quad_perm:[2,3,0,1] row_mask:0xf bank_mask:0xf
	s_nop 1
	v_add_f32_dpp v103, v103, v103 row_half_mirror row_mask:0xf bank_mask:0xf
	s_nop 1
	v_add_f32_dpp v103, v103, v103 row_mirror row_mask:0xf bank_mask:0xf
	v_mov_b32_e32 v104, v103
	s_nop 1
	v_permlane16_swap_b32_e32 v103, v104
	s_nop 0
	v_add_f32_e32 v103, v103, v104
	v_mov_b32_e32 v104, v103
	s_nop 1
	v_permlane32_swap_b32_e32 v103, v104
	s_nop 0
	v_add_f32_e32 v103, v103, v104
	v_fma_f32 v103, v103, s37, v108
	v_rsq_f32_e32 v107, v103
	s_nop 0
	v_mul_f32_e32 v34, v34, v107
	v_mul_f32_e32 v35, v35, v107
	v_mul_f32_e32 v36, v36, v107
	v_mul_f32_e32 v37, v37, v107
	v_mul_f32_e32 v38, v38, v107
	v_mul_f32_e32 v39, v39, v107
	v_mul_f32_e32 v40, v40, v107
	v_mul_f32_e32 v41, v41, v107
	v_mul_f32_e32 v42, v42, v107
	v_mul_f32_e32 v43, v43, v107
	v_mul_f32_e32 v44, v44, v107
	v_mul_f32_e32 v45, v45, v107
	v_mul_f32_e32 v46, v46, v107
	v_mul_f32_e32 v47, v47, v107
	v_mul_f32_e32 v48, v48, v107
	v_mul_f32_e32 v49, v49, v107
	v_fma_f32 v34, v34, v66, v82
	v_fma_f32 v35, v35, v67, v83
	v_fma_f32 v36, v36, v68, v84
	v_fma_f32 v37, v37, v69, v85
	v_fma_f32 v38, v38, v70, v86
	v_fma_f32 v39, v39, v71, v87
	v_fma_f32 v40, v40, v72, v88
	v_fma_f32 v41, v41, v73, v89
	v_fma_f32 v42, v42, v74, v90
	v_fma_f32 v43, v43, v75, v91
	v_fma_f32 v44, v44, v76, v92
	v_fma_f32 v45, v45, v77, v93
	v_fma_f32 v46, v46, v78, v94
	v_fma_f32 v47, v47, v79, v95
	v_fma_f32 v48, v48, v80, v96
	v_fma_f32 v49, v49, v81, v97
	v_cvt_pk_bf16_f32 v110, v34, v35
	v_cvt_pk_bf16_f32 v111, v36, v37
	v_cvt_pk_bf16_f32 v112, v38, v39
	v_cvt_pk_bf16_f32 v113, v40, v41
	v_cvt_pk_bf16_f32 v114, v42, v43
	v_cvt_pk_bf16_f32 v115, v44, v45
	v_cvt_pk_bf16_f32 v116, v46, v47
	v_cvt_pk_bf16_f32 v117, v48, v49
	global_store_dwordx2 v101, v[110:111], s[30:31]
	global_store_dwordx2 v101, v[112:113], s[30:31] offset:512
	global_store_dwordx2 v101, v[114:115], s[30:31] offset:1024
	global_store_dwordx2 v101, v[116:117], s[30:31] offset:1536
	s_mov_b64 exec, s[0:1]
	global_store_dwordx2 v109, v[106:107], s[32:33]
	s_mov_b64 exec, -1
	s_add_u32 s30, s30, s35
	s_addc_u32 s31, s31, 0
	s_add_u32 s32, s32, s36
	s_addc_u32 s33, s33, 0
	s_waitcnt vmcnt(23)
	global_load_dwordx4 v[34:37], v100, s[28:29] nt
	global_load_dwordx4 v[38:41], v100, s[28:29] offset:1024 nt
	global_load_dwordx4 v[42:45], v100, s[28:29] offset:2048 nt
	global_load_dwordx4 v[46:49], v100, s[28:29] offset:3072 nt
	s_add_u32 s28, s28, s34
	s_addc_u32 s29, s29, 0
	v_add_f32_e32 v104, v50, v51
	v_add_f32_e32 v105, v52, v53
	v_add_f32_e32 v104, v104, v105
	v_mov_b32_e32 v102, v104
	v_add_f32_e32 v104, v54, v55
	v_add_f32_e32 v105, v56, v57
	v_add_f32_e32 v104, v104, v105
	v_add_f32_e32 v102, v102, v104
	v_add_f32_e32 v104, v58, v59
	v_add_f32_e32 v105, v60, v61
	v_add_f32_e32 v104, v104, v105
	v_add_f32_e32 v102, v102, v104
	v_add_f32_e32 v104, v62, v63
	v_add_f32_e32 v105, v64, v65
	v_add_f32_e32 v104, v104, v105
	v_add_f32_e32 v102, v102, v104
	s_nop 1
	v_add_f32_dpp v102, v102, v102 quad_perm:[1,0,3,2] row_mask:0xf bank_mask:0xf
	s_nop 1
	v_add_f32_dpp v102, v102, v102 quad_perm:[2,3,0,1] row_mask:0xf bank_mask:0xf
	s_nop 1
	v_add_f32_dpp v102, v102, v102 row_half_mirror row_mask:0xf bank_mask:0xf
	s_nop 1
	v_add_f32_dpp v102, v102, v102 row_mirror row_mask:0xf bank_mask:0xf
	v_mov_b32_e32 v104, v102
	s_nop 1
	v_permlane16_swap_b32_e32 v102, v104
	s_nop 0
	v_add_f32_e32 v102, v102, v104
	v_mov_b32_e32 v104, v102
	s_nop 1
	v_permlane32_swap_b32_e32 v102, v104
	s_nop 0
	v_add_f32_e32 v102, v102, v104
	v_mul_f32_e32 v106, 0x3a800000, v102
	v_sub_f32_e32 v50, v50, v106
	v_sub_f32_e32 v51, v51, v106
	v_sub_f32_e32 v52, v52, v106
	v_sub_f32_e32 v53, v53, v106
	v_sub_f32_e32 v54, v54, v106
	v_sub_f32_e32 v55, v55, v106
	v_sub_f32_e32 v56, v56, v106
	v_sub_f32_e32 v57, v57, v106
	v_sub_f32_e32 v58, v58, v106
	v_sub_f32_e32 v59, v59, v106
	v_sub_f32_e32 v60, v60, v106
	v_sub_f32_e32 v61, v61, v106
	v_sub_f32_e32 v62, v62, v106
	v_sub_f32_e32 v63, v63, v106
	v_sub_f32_e32 v64, v64, v106
	v_sub_f32_e32 v65, v65, v106
	v_mul_f32_e32 v104, v50, v50
	v_mul_f32_e32 v105, v52, v52
	v_fmac_f32_e32 v104, v51, v51
	v_fmac_f32_e32 v105, v53, v53
	v_add_f32_e32 v104, v104, v105
	v_mov_b32_e32 v103, v104
	v_mul_f32_e32 v104, v54, v54
	v_mul_f32_e32 v105, v56, v56
	v_fmac_f32_e32 v104, v55, v55
	v_fmac_f32_e32 v105, v57, v57
	v_add_f32_e32 v104, v104, v105
	v_add_f32_e32 v103, v103, v104
	v_mul_f32_e32 v104, v58, v58
	v_mul_f32_e32 v105, v60, v60
	v_fmac_f32_e32 v104, v59, v59
	v_fmac_f32_e32 v105, v61, v61
	v_add_f32_e32 v104, v104, v105
	v_add_f32_e32 v103, v103, v104
	v_mul_f32_e32 v104, v62, v62
	v_mul_f32_e32 v105, v64, v64
	v_fmac_f32_e32 v104, v63, v63
	v_fmac_f32_e32 v105, v65, v65
	v_add_f32_e32 v104, v104, v105
	v_add_f32_e32 v103, v103, v104
	s_nop 1
	v_add_f32_dpp v103, v103, v103 quad_perm:[1,0,3,2] row_mask:0xf bank_mask:0xf
	s_nop 1
	v_add_f32_dpp v103, v103, v103 quad_perm:[2,3,0,1] row_mask:0xf bank_mask:0xf
	s_nop 1
	v_add_f32_dpp v103, v103, v103 row_half_mirror row_mask:0xf bank_mask:0xf
	s_nop 1
	v_add_f32_dpp v103, v103, v103 row_mirror row_mask:0xf bank_mask:0xf
	v_mov_b32_e32 v104, v103
	s_nop 1
	v_permlane16_swap_b32_e32 v103, v104
	s_nop 0
	v_add_f32_e32 v103, v103, v104
	v_mov_b32_e32 v104, v103
	s_nop 1
	v_permlane32_swap_b32_e32 v103, v104
	s_nop 0
	v_add_f32_e32 v103, v103, v104
	v_fma_f32 v103, v103, s37, v108
	v_rsq_f32_e32 v107, v103
	s_nop 0
	v_mul_f32_e32 v50, v50, v107
	v_mul_f32_e32 v51, v51, v107
	v_mul_f32_e32 v52, v52, v107
	v_mul_f32_e32 v53, v53, v107
	v_mul_f32_e32 v54, v54, v107
	v_mul_f32_e32 v55, v55, v107
	v_mul_f32_e32 v56, v56, v107
	v_mul_f32_e32 v57, v57, v107
	v_mul_f32_e32 v58, v58, v107
	v_mul_f32_e32 v59, v59, v107
	v_mul_f32_e32 v60, v60, v107
	v_mul_f32_e32 v61, v61, v107
	v_mul_f32_e32 v62, v62, v107
	v_mul_f32_e32 v63, v63, v107
	v_mul_f32_e32 v64, v64, v107
	v_mul_f32_e32 v65, v65, v107
	v_fma_f32 v50, v50, v66, v82
	v_fma_f32 v51, v51, v67, v83
	v_fma_f32 v52, v52, v68, v84
	v_fma_f32 v53, v53, v69, v85
	v_fma_f32 v54, v54, v70, v86
	v_fma_f32 v55, v55, v71, v87
	v_fma_f32 v56, v56, v72, v88
	v_fma_f32 v57, v57, v73, v89
	v_fma_f32 v58, v58, v74, v90
	v_fma_f32 v59, v59, v75, v91
	v_fma_f32 v60, v60, v76, v92
	v_fma_f32 v61, v61, v77, v93
	v_fma_f32 v62, v62, v78, v94
	v_fma_f32 v63, v63, v79, v95
	v_fma_f32 v64, v64, v80, v96
	v_fma_f32 v65, v65, v81, v97
	v_cvt_pk_bf16_f32 v110, v50, v51
	v_cvt_pk_bf16_f32 v111, v52, v53
	v_cvt_pk_bf16_f32 v112, v54, v55
	v_cvt_pk_bf16_f32 v113, v56, v57
	v_cvt_pk_bf16_f32 v114, v58, v59
	v_cvt_pk_bf16_f32 v115, v60, v61
	v_cvt_pk_bf16_f32 v116, v62, v63
	v_cvt_pk_bf16_f32 v117, v64, v65
	global_store_dwordx2 v101, v[110:111], s[30:31]
	global_store_dwordx2 v101, v[112:113], s[30:31] offset:512
	global_store_dwordx2 v101, v[114:115], s[30:31] offset:1024
	global_store_dwordx2 v101, v[116:117], s[30:31] offset:1536
	s_mov_b64 exec, s[0:1]
	global_store_dwordx2 v109, v[106:107], s[32:33]
	s_mov_b64 exec, -1
	s_add_u32 s30, s30, s35
	s_addc_u32 s31, s31, 0
	s_add_u32 s32, s32, s36
	s_addc_u32 s33, s33, 0
	s_waitcnt vmcnt(23)
	global_load_dwordx4 v[50:53], v100, s[28:29] nt
	global_load_dwordx4 v[54:57], v100, s[28:29] offset:1024 nt
	global_load_dwordx4 v[58:61], v100, s[28:29] offset:2048 nt
	global_load_dwordx4 v[62:65], v100, s[28:29] offset:3072 nt
	s_add_u32 s28, s28, s34
	s_addc_u32 s29, s29, 0
	v_add_f32_e32 v104, v2, v3
	v_add_f32_e32 v105, v4, v5
	v_add_f32_e32 v104, v104, v105
	v_mov_b32_e32 v102, v104
	v_add_f32_e32 v104, v6, v7
	v_add_f32_e32 v105, v8, v9
	v_add_f32_e32 v104, v104, v105
	v_add_f32_e32 v102, v102, v104
	v_add_f32_e32 v104, v10, v11
	v_add_f32_e32 v105, v12, v13
	v_add_f32_e32 v104, v104, v105
	v_add_f32_e32 v102, v102, v104
	v_add_f32_e32 v104, v14, v15
	v_add_f32_e32 v105, v16, v17
	v_add_f32_e32 v104, v104, v105
	v_add_f32_e32 v102, v102, v104
	s_nop 1
	v_add_f32_dpp v102, v102, v102 quad_perm:[1,0,3,2] row_mask:0xf bank_mask:0xf
	s_nop 1
	v_add_f32_dpp v102, v102, v102 quad_perm:[2,3,0,1] row_mask:0xf bank_mask:0xf
	s_nop 1
	v_add_f32_dpp v102, v102, v102 row_half_mirror row_mask:0xf bank_mask:0xf
	s_nop 1
	v_add_f32_dpp v102, v102, v102 row_mirror row_mask:0xf bank_mask:0xf
	v_mov_b32_e32 v104, v102
	s_nop 1
	v_permlane16_swap_b32_e32 v102, v104
	s_nop 0
	v_add_f32_e32 v102, v102, v104
	v_mov_b32_e32 v104, v102
	s_nop 1
	v_permlane32_swap_b32_e32 v102, v104
	s_nop 0
	v_add_f32_e32 v102, v102, v104
	v_mul_f32_e32 v106, 0x3a800000, v102
	v_sub_f32_e32 v2, v2, v106
	v_sub_f32_e32 v3, v3, v106
	v_sub_f32_e32 v4, v4, v106
	v_sub_f32_e32 v5, v5, v106
	v_sub_f32_e32 v6, v6, v106
	v_sub_f32_e32 v7, v7, v106
	v_sub_f32_e32 v8, v8, v106
	v_sub_f32_e32 v9, v9, v106
	v_sub_f32_e32 v10, v10, v106
	v_sub_f32_e32 v11, v11, v106
	v_sub_f32_e32 v12, v12, v106
	v_sub_f32_e32 v13, v13, v106
	v_sub_f32_e32 v14, v14, v106
	v_sub_f32_e32 v15, v15, v106
	v_sub_f32_e32 v16, v16, v106
	v_sub_f32_e32 v17, v17, v106
	v_mul_f32_e32 v104, v2, v2
	v_mul_f32_e32 v105, v4, v4
	v_fmac_f32_e32 v104, v3, v3
	v_fmac_f32_e32 v105, v5, v5
	v_add_f32_e32 v104, v104, v105
	v_mov_b32_e32 v103, v104
	v_mul_f32_e32 v104, v6, v6
	v_mul_f32_e32 v105, v8, v8
	v_fmac_f32_e32 v104, v7, v7
	v_fmac_f32_e32 v105, v9, v9
	v_add_f32_e32 v104, v104, v105
	v_add_f32_e32 v103, v103, v104
	v_mul_f32_e32 v104, v10, v10
	v_mul_f32_e32 v105, v12, v12
	v_fmac_f32_e32 v104, v11, v11
	v_fmac_f32_e32 v105, v13, v13
	v_add_f32_e32 v104, v104, v105
	v_add_f32_e32 v103, v103, v104
	v_mul_f32_e32 v104, v14, v14
	v_mul_f32_e32 v105, v16, v16
	v_fmac_f32_e32 v104, v15, v15
	v_fmac_f32_e32 v105, v17, v17
	v_add_f32_e32 v104, v104, v105
	v_add_f32_e32 v103, v103, v104
	s_nop 1
	v_add_f32_dpp v103, v103, v103 quad_perm:[1,0,3,2] row_mask:0xf bank_mask:0xf
	s_nop 1
	v_add_f32_dpp v103, v103, v103 quad_perm:[2,3,0,1] row_mask:0xf bank_mask:0xf
	s_nop 1
	v_add_f32_dpp v103, v103, v103 row_half_mirror row_mask:0xf bank_mask:0xf
	s_nop 1
	v_add_f32_dpp v103, v103, v103 row_mirror row_mask:0xf bank_mask:0xf
	v_mov_b32_e32 v104, v103
	s_nop 1
	v_permlane16_swap_b32_e32 v103, v104
	s_nop 0
	v_add_f32_e32 v103, v103, v104
	v_mov_b32_e32 v104, v103
	s_nop 1
	v_permlane32_swap_b32_e32 v103, v104
	s_nop 0
	v_add_f32_e32 v103, v103, v104
	v_fma_f32 v103, v103, s37, v108
	v_rsq_f32_e32 v107, v103
	s_nop 0
	v_mul_f32_e32 v2, v2, v107
	v_mul_f32_e32 v3, v3, v107
	v_mul_f32_e32 v4, v4, v107
	v_mul_f32_e32 v5, v5, v107
	v_mul_f32_e32 v6, v6, v107
	v_mul_f32_e32 v7, v7, v107
	v_mul_f32_e32 v8, v8, v107
	v_mul_f32_e32 v9, v9, v107
	v_mul_f32_e32 v10, v10, v107
	v_mul_f32_e32 v11, v11, v107
	v_mul_f32_e32 v12, v12, v107
	v_mul_f32_e32 v13, v13, v107
	v_mul_f32_e32 v14, v14, v107
	v_mul_f32_e32 v15, v15, v107
	v_mul_f32_e32 v16, v16, v107
	v_mul_f32_e32 v17, v17, v107
	v_fma_f32 v2, v2, v66, v82
	v_fma_f32 v3, v3, v67, v83
	v_fma_f32 v4, v4, v68, v84
	v_fma_f32 v5, v5, v69, v85
	v_fma_f32 v6, v6, v70, v86
	v_fma_f32 v7, v7, v71, v87
	v_fma_f32 v8, v8, v72, v88
	v_fma_f32 v9, v9, v73, v89
	v_fma_f32 v10, v10, v74, v90
	v_fma_f32 v11, v11, v75, v91
	v_fma_f32 v12, v12, v76, v92
	v_fma_f32 v13, v13, v77, v93
	v_fma_f32 v14, v14, v78, v94
	v_fma_f32 v15, v15, v79, v95
	v_fma_f32 v16, v16, v80, v96
	v_fma_f32 v17, v17, v81, v97
	v_cvt_pk_bf16_f32 v110, v2, v3
	v_cvt_pk_bf16_f32 v111, v4, v5
	v_cvt_pk_bf16_f32 v112, v6, v7
	v_cvt_pk_bf16_f32 v113, v8, v9
	v_cvt_pk_bf16_f32 v114, v10, v11
	v_cvt_pk_bf16_f32 v115, v12, v13
	v_cvt_pk_bf16_f32 v116, v14, v15
	v_cvt_pk_bf16_f32 v117, v16, v17
	global_store_dwordx2 v101, v[110:111], s[30:31]
	global_store_dwordx2 v101, v[112:113], s[30:31] offset:512
	global_store_dwordx2 v101, v[114:115], s[30:31] offset:1024
	global_store_dwordx2 v101, v[116:117], s[30:31] offset:1536
	s_mov_b64 exec, s[0:1]
	global_store_dwordx2 v109, v[106:107], s[32:33]
	s_mov_b64 exec, -1
	s_add_u32 s30, s30, s35
	s_addc_u32 s31, s31, 0
	s_add_u32 s32, s32, s36
	s_addc_u32 s33, s33, 0
	s_waitcnt vmcnt(23)
	global_load_dwordx4 v[2:5], v100, s[28:29] nt
	global_load_dwordx4 v[6:9], v100, s[28:29] offset:1024 nt
	global_load_dwordx4 v[10:13], v100, s[28:29] offset:2048 nt
	global_load_dwordx4 v[14:17], v100, s[28:29] offset:3072 nt
	s_add_u32 s28, s28, s34
	s_addc_u32 s29, s29, 0
	v_add_f32_e32 v104, v18, v19
	v_add_f32_e32 v105, v20, v21
	v_add_f32_e32 v104, v104, v105
	v_mov_b32_e32 v102, v104
	v_add_f32_e32 v104, v22, v23
	v_add_f32_e32 v105, v24, v25
	v_add_f32_e32 v104, v104, v105
	v_add_f32_e32 v102, v102, v104
	v_add_f32_e32 v104, v26, v27
	v_add_f32_e32 v105, v28, v29
	v_add_f32_e32 v104, v104, v105
	v_add_f32_e32 v102, v102, v104
	v_add_f32_e32 v104, v30, v31
	v_add_f32_e32 v105, v32, v33
	v_add_f32_e32 v104, v104, v105
	v_add_f32_e32 v102, v102, v104
	s_nop 1
	v_add_f32_dpp v102, v102, v102 quad_perm:[1,0,3,2] row_mask:0xf bank_mask:0xf
	s_nop 1
	v_add_f32_dpp v102, v102, v102 quad_perm:[2,3,0,1] row_mask:0xf bank_mask:0xf
	s_nop 1
	v_add_f32_dpp v102, v102, v102 row_half_mirror row_mask:0xf bank_mask:0xf
	s_nop 1
	v_add_f32_dpp v102, v102, v102 row_mirror row_mask:0xf bank_mask:0xf
	v_mov_b32_e32 v104, v102
	s_nop 1
	v_permlane16_swap_b32_e32 v102, v104
	s_nop 0
	v_add_f32_e32 v102, v102, v104
	v_mov_b32_e32 v104, v102
	s_nop 1
	v_permlane32_swap_b32_e32 v102, v104
	s_nop 0
	v_add_f32_e32 v102, v102, v104
	v_mul_f32_e32 v106, 0x3a800000, v102
	v_sub_f32_e32 v18, v18, v106
	v_sub_f32_e32 v19, v19, v106
	v_sub_f32_e32 v20, v20, v106
	v_sub_f32_e32 v21, v21, v106
	v_sub_f32_e32 v22, v22, v106
	v_sub_f32_e32 v23, v23, v106
	v_sub_f32_e32 v24, v24, v106
	v_sub_f32_e32 v25, v25, v106
	v_sub_f32_e32 v26, v26, v106
	v_sub_f32_e32 v27, v27, v106
	v_sub_f32_e32 v28, v28, v106
	v_sub_f32_e32 v29, v29, v106
	v_sub_f32_e32 v30, v30, v106
	v_sub_f32_e32 v31, v31, v106
	v_sub_f32_e32 v32, v32, v106
	v_sub_f32_e32 v33, v33, v106
	v_mul_f32_e32 v104, v18, v18
	v_mul_f32_e32 v105, v20, v20
	v_fmac_f32_e32 v104, v19, v19
	v_fmac_f32_e32 v105, v21, v21
	v_add_f32_e32 v104, v104, v105
	v_mov_b32_e32 v103, v104
	v_mul_f32_e32 v104, v22, v22
	v_mul_f32_e32 v105, v24, v24
	v_fmac_f32_e32 v104, v23, v23
	v_fmac_f32_e32 v105, v25, v25
	v_add_f32_e32 v104, v104, v105
	v_add_f32_e32 v103, v103, v104
	v_mul_f32_e32 v104, v26, v26
	v_mul_f32_e32 v105, v28, v28
	v_fmac_f32_e32 v104, v27, v27
	v_fmac_f32_e32 v105, v29, v29
	v_add_f32_e32 v104, v104, v105
	v_add_f32_e32 v103, v103, v104
	v_mul_f32_e32 v104, v30, v30
	v_mul_f32_e32 v105, v32, v32
	v_fmac_f32_e32 v104, v31, v31
	v_fmac_f32_e32 v105, v33, v33
	v_add_f32_e32 v104, v104, v105
	v_add_f32_e32 v103, v103, v104
	s_nop 1
	v_add_f32_dpp v103, v103, v103 quad_perm:[1,0,3,2] row_mask:0xf bank_mask:0xf
	s_nop 1
	v_add_f32_dpp v103, v103, v103 quad_perm:[2,3,0,1] row_mask:0xf bank_mask:0xf
	s_nop 1
	v_add_f32_dpp v103, v103, v103 row_half_mirror row_mask:0xf bank_mask:0xf
	s_nop 1
	v_add_f32_dpp v103, v103, v103 row_mirror row_mask:0xf bank_mask:0xf
	v_mov_b32_e32 v104, v103
	s_nop 1
	v_permlane16_swap_b32_e32 v103, v104
	s_nop 0
	v_add_f32_e32 v103, v103, v104
	v_mov_b32_e32 v104, v103
	s_nop 1
	v_permlane32_swap_b32_e32 v103, v104
	s_nop 0
	v_add_f32_e32 v103, v103, v104
	v_fma_f32 v103, v103, s37, v108
	v_rsq_f32_e32 v107, v103
	s_nop 0
	v_mul_f32_e32 v18, v18, v107
	v_mul_f32_e32 v19, v19, v107
	v_mul_f32_e32 v20, v20, v107
	v_mul_f32_e32 v21, v21, v107
	v_mul_f32_e32 v22, v22, v107
	v_mul_f32_e32 v23, v23, v107
	v_mul_f32_e32 v24, v24, v107
	v_mul_f32_e32 v25, v25, v107
	v_mul_f32_e32 v26, v26, v107
	v_mul_f32_e32 v27, v27, v107
	v_mul_f32_e32 v28, v28, v107
	v_mul_f32_e32 v29, v29, v107
	v_mul_f32_e32 v30, v30, v107
	v_mul_f32_e32 v31, v31, v107
	v_mul_f32_e32 v32, v32, v107
	v_mul_f32_e32 v33, v33, v107
	v_fma_f32 v18, v18, v66, v82
	v_fma_f32 v19, v19, v67, v83
	v_fma_f32 v20, v20, v68, v84
	v_fma_f32 v21, v21, v69, v85
	v_fma_f32 v22, v22, v70, v86
	v_fma_f32 v23, v23, v71, v87
	v_fma_f32 v24, v24, v72, v88
	v_fma_f32 v25, v25, v73, v89
	v_fma_f32 v26, v26, v74, v90
	v_fma_f32 v27, v27, v75, v91
	v_fma_f32 v28, v28, v76, v92
	v_fma_f32 v29, v29, v77, v93
	v_fma_f32 v30, v30, v78, v94
	v_fma_f32 v31, v31, v79, v95
	v_fma_f32 v32, v32, v80, v96
	v_fma_f32 v33, v33, v81, v97
	v_cvt_pk_bf16_f32 v110, v18, v19
	v_cvt_pk_bf16_f32 v111, v20, v21
	v_cvt_pk_bf16_f32 v112, v22, v23
	v_cvt_pk_bf16_f32 v113, v24, v25
	v_cvt_pk_bf16_f32 v114, v26, v27
	v_cvt_pk_bf16_f32 v115, v28, v29
	v_cvt_pk_bf16_f32 v116, v30, v31
	v_cvt_pk_bf16_f32 v117, v32, v33
	global_store_dwordx2 v101, v[110:111], s[30:31]
	global_store_dwordx2 v101, v[112:113], s[30:31] offset:512
	global_store_dwordx2 v101, v[114:115], s[30:31] offset:1024
	global_store_dwordx2 v101, v[116:117], s[30:31] offset:1536
	s_mov_b64 exec, s[0:1]
	global_store_dwordx2 v109, v[106:107], s[32:33]
	s_mov_b64 exec, -1
	s_add_u32 s30, s30, s35
	s_addc_u32 s31, s31, 0
	s_add_u32 s32, s32, s36
	s_addc_u32 s33, s33, 0
	s_waitcnt vmcnt(23)
	global_load_dwordx4 v[18:21], v100, s[28:29] nt
	global_load_dwordx4 v[22:25], v100, s[28:29] offset:1024 nt
	global_load_dwordx4 v[26:29], v100, s[28:29] offset:2048 nt
	global_load_dwordx4 v[30:33], v100, s[28:29] offset:3072 nt
	s_add_u32 s28, s28, s34
	s_addc_u32 s29, s29, 0
	v_add_f32_e32 v104, v34, v35
	v_add_f32_e32 v105, v36, v37
	v_add_f32_e32 v104, v104, v105
	v_mov_b32_e32 v102, v104
	v_add_f32_e32 v104, v38, v39
	v_add_f32_e32 v105, v40, v41
	v_add_f32_e32 v104, v104, v105
	v_add_f32_e32 v102, v102, v104
	v_add_f32_e32 v104, v42, v43
	v_add_f32_e32 v105, v44, v45
	v_add_f32_e32 v104, v104, v105
	v_add_f32_e32 v102, v102, v104
	v_add_f32_e32 v104, v46, v47
	v_add_f32_e32 v105, v48, v49
	v_add_f32_e32 v104, v104, v105
	v_add_f32_e32 v102, v102, v104
	s_nop 1
	v_add_f32_dpp v102, v102, v102 quad_perm:[1,0,3,2] row_mask:0xf bank_mask:0xf
	s_nop 1
	v_add_f32_dpp v102, v102, v102 quad_perm:[2,3,0,1] row_mask:0xf bank_mask:0xf
	s_nop 1
	v_add_f32_dpp v102, v102, v102 row_half_mirror row_mask:0xf bank_mask:0xf
	s_nop 1
	v_add_f32_dpp v102, v102, v102 row_mirror row_mask:0xf bank_mask:0xf
	v_mov_b32_e32 v104, v102
	s_nop 1
	v_permlane16_swap_b32_e32 v102, v104
	s_nop 0
	v_add_f32_e32 v102, v102, v104
	v_mov_b32_e32 v104, v102
	s_nop 1
	v_permlane32_swap_b32_e32 v102, v104
	s_nop 0
	v_add_f32_e32 v102, v102, v104
	v_mul_f32_e32 v106, 0x3a800000, v102
	v_sub_f32_e32 v34, v34, v106
	v_sub_f32_e32 v35, v35, v106
	v_sub_f32_e32 v36, v36, v106
	v_sub_f32_e32 v37, v37, v106
	v_sub_f32_e32 v38, v38, v106
	v_sub_f32_e32 v39, v39, v106
	v_sub_f32_e32 v40, v40, v106
	v_sub_f32_e32 v41, v41, v106
	v_sub_f32_e32 v42, v42, v106
	v_sub_f32_e32 v43, v43, v106
	v_sub_f32_e32 v44, v44, v106
	v_sub_f32_e32 v45, v45, v106
	v_sub_f32_e32 v46, v46, v106
	v_sub_f32_e32 v47, v47, v106
	v_sub_f32_e32 v48, v48, v106
	v_sub_f32_e32 v49, v49, v106
	v_mul_f32_e32 v104, v34, v34
	v_mul_f32_e32 v105, v36, v36
	v_fmac_f32_e32 v104, v35, v35
	v_fmac_f32_e32 v105, v37, v37
	v_add_f32_e32 v104, v104, v105
	v_mov_b32_e32 v103, v104
	v_mul_f32_e32 v104, v38, v38
	v_mul_f32_e32 v105, v40, v40
	v_fmac_f32_e32 v104, v39, v39
	v_fmac_f32_e32 v105, v41, v41
	v_add_f32_e32 v104, v104, v105
	v_add_f32_e32 v103, v103, v104
	v_mul_f32_e32 v104, v42, v42
	v_mul_f32_e32 v105, v44, v44
	v_fmac_f32_e32 v104, v43, v43
	v_fmac_f32_e32 v105, v45, v45
	v_add_f32_e32 v104, v104, v105
	v_add_f32_e32 v103, v103, v104
	v_mul_f32_e32 v104, v46, v46
	v_mul_f32_e32 v105, v48, v48
	v_fmac_f32_e32 v104, v47, v47
	v_fmac_f32_e32 v105, v49, v49
	v_add_f32_e32 v104, v104, v105
	v_add_f32_e32 v103, v103, v104
	s_nop 1
	v_add_f32_dpp v103, v103, v103 quad_perm:[1,0,3,2] row_mask:0xf bank_mask:0xf
	s_nop 1
	v_add_f32_dpp v103, v103, v103 quad_perm:[2,3,0,1] row_mask:0xf bank_mask:0xf
	s_nop 1
	v_add_f32_dpp v103, v103, v103 row_half_mirror row_mask:0xf bank_mask:0xf
	s_nop 1
	v_add_f32_dpp v103, v103, v103 row_mirror row_mask:0xf bank_mask:0xf
	v_mov_b32_e32 v104, v103
	s_nop 1
	v_permlane16_swap_b32_e32 v103, v104
	s_nop 0
	v_add_f32_e32 v103, v103, v104
	v_mov_b32_e32 v104, v103
	s_nop 1
	v_permlane32_swap_b32_e32 v103, v104
	s_nop 0
	v_add_f32_e32 v103, v103, v104
	v_fma_f32 v103, v103, s37, v108
	v_rsq_f32_e32 v107, v103
	s_nop 0
	v_mul_f32_e32 v34, v34, v107
	v_mul_f32_e32 v35, v35, v107
	v_mul_f32_e32 v36, v36, v107
	v_mul_f32_e32 v37, v37, v107
	v_mul_f32_e32 v38, v38, v107
	v_mul_f32_e32 v39, v39, v107
	v_mul_f32_e32 v40, v40, v107
	v_mul_f32_e32 v41, v41, v107
	v_mul_f32_e32 v42, v42, v107
	v_mul_f32_e32 v43, v43, v107
	v_mul_f32_e32 v44, v44, v107
	v_mul_f32_e32 v45, v45, v107
	v_mul_f32_e32 v46, v46, v107
	v_mul_f32_e32 v47, v47, v107
	v_mul_f32_e32 v48, v48, v107
	v_mul_f32_e32 v49, v49, v107
	v_fma_f32 v34, v34, v66, v82
	v_fma_f32 v35, v35, v67, v83
	v_fma_f32 v36, v36, v68, v84
	v_fma_f32 v37, v37, v69, v85
	v_fma_f32 v38, v38, v70, v86
	v_fma_f32 v39, v39, v71, v87
	v_fma_f32 v40, v40, v72, v88
	v_fma_f32 v41, v41, v73, v89
	v_fma_f32 v42, v42, v74, v90
	v_fma_f32 v43, v43, v75, v91
	v_fma_f32 v44, v44, v76, v92
	v_fma_f32 v45, v45, v77, v93
	v_fma_f32 v46, v46, v78, v94
	v_fma_f32 v47, v47, v79, v95
	v_fma_f32 v48, v48, v80, v96
	v_fma_f32 v49, v49, v81, v97
	v_cvt_pk_bf16_f32 v110, v34, v35
	v_cvt_pk_bf16_f32 v111, v36, v37
	v_cvt_pk_bf16_f32 v112, v38, v39
	v_cvt_pk_bf16_f32 v113, v40, v41
	v_cvt_pk_bf16_f32 v114, v42, v43
	v_cvt_pk_bf16_f32 v115, v44, v45
	v_cvt_pk_bf16_f32 v116, v46, v47
	v_cvt_pk_bf16_f32 v117, v48, v49
	global_store_dwordx2 v101, v[110:111], s[30:31]
	global_store_dwordx2 v101, v[112:113], s[30:31] offset:512
	global_store_dwordx2 v101, v[114:115], s[30:31] offset:1024
	global_store_dwordx2 v101, v[116:117], s[30:31] offset:1536
	s_mov_b64 exec, s[0:1]
	global_store_dwordx2 v109, v[106:107], s[32:33]
	s_mov_b64 exec, -1
	s_add_u32 s30, s30, s35
	s_addc_u32 s31, s31, 0
	s_add_u32 s32, s32, s36
	s_addc_u32 s33, s33, 0
	s_waitcnt vmcnt(23)
	global_load_dwordx4 v[34:37], v100, s[28:29] nt
	global_load_dwordx4 v[38:41], v100, s[28:29] offset:1024 nt
	global_load_dwordx4 v[42:45], v100, s[28:29] offset:2048 nt
	global_load_dwordx4 v[46:49], v100, s[28:29] offset:3072 nt
	s_add_u32 s28, s28, s34
	s_addc_u32 s29, s29, 0
	v_add_f32_e32 v104, v50, v51
	v_add_f32_e32 v105, v52, v53
	v_add_f32_e32 v104, v104, v105
	v_mov_b32_e32 v102, v104
	v_add_f32_e32 v104, v54, v55
	v_add_f32_e32 v105, v56, v57
	v_add_f32_e32 v104, v104, v105
	v_add_f32_e32 v102, v102, v104
	v_add_f32_e32 v104, v58, v59
	v_add_f32_e32 v105, v60, v61
	v_add_f32_e32 v104, v104, v105
	v_add_f32_e32 v102, v102, v104
	v_add_f32_e32 v104, v62, v63
	v_add_f32_e32 v105, v64, v65
	v_add_f32_e32 v104, v104, v105
	v_add_f32_e32 v102, v102, v104
	s_nop 1
	v_add_f32_dpp v102, v102, v102 quad_perm:[1,0,3,2] row_mask:0xf bank_mask:0xf
	s_nop 1
	v_add_f32_dpp v102, v102, v102 quad_perm:[2,3,0,1] row_mask:0xf bank_mask:0xf
	s_nop 1
	v_add_f32_dpp v102, v102, v102 row_half_mirror row_mask:0xf bank_mask:0xf
	s_nop 1
	v_add_f32_dpp v102, v102, v102 row_mirror row_mask:0xf bank_mask:0xf
	v_mov_b32_e32 v104, v102
	s_nop 1
	v_permlane16_swap_b32_e32 v102, v104
	s_nop 0
	v_add_f32_e32 v102, v102, v104
	v_mov_b32_e32 v104, v102
	s_nop 1
	v_permlane32_swap_b32_e32 v102, v104
	s_nop 0
	v_add_f32_e32 v102, v102, v104
	v_mul_f32_e32 v106, 0x3a800000, v102
	v_sub_f32_e32 v50, v50, v106
	v_sub_f32_e32 v51, v51, v106
	v_sub_f32_e32 v52, v52, v106
	v_sub_f32_e32 v53, v53, v106
	v_sub_f32_e32 v54, v54, v106
	v_sub_f32_e32 v55, v55, v106
	v_sub_f32_e32 v56, v56, v106
	v_sub_f32_e32 v57, v57, v106
	v_sub_f32_e32 v58, v58, v106
	v_sub_f32_e32 v59, v59, v106
	v_sub_f32_e32 v60, v60, v106
	v_sub_f32_e32 v61, v61, v106
	v_sub_f32_e32 v62, v62, v106
	v_sub_f32_e32 v63, v63, v106
	v_sub_f32_e32 v64, v64, v106
	v_sub_f32_e32 v65, v65, v106
	v_mul_f32_e32 v104, v50, v50
	v_mul_f32_e32 v105, v52, v52
	v_fmac_f32_e32 v104, v51, v51
	v_fmac_f32_e32 v105, v53, v53
	v_add_f32_e32 v104, v104, v105
	v_mov_b32_e32 v103, v104
	v_mul_f32_e32 v104, v54, v54
	v_mul_f32_e32 v105, v56, v56
	v_fmac_f32_e32 v104, v55, v55
	v_fmac_f32_e32 v105, v57, v57
	v_add_f32_e32 v104, v104, v105
	v_add_f32_e32 v103, v103, v104
	v_mul_f32_e32 v104, v58, v58
	v_mul_f32_e32 v105, v60, v60
	v_fmac_f32_e32 v104, v59, v59
	v_fmac_f32_e32 v105, v61, v61
	v_add_f32_e32 v104, v104, v105
	v_add_f32_e32 v103, v103, v104
	v_mul_f32_e32 v104, v62, v62
	v_mul_f32_e32 v105, v64, v64
	v_fmac_f32_e32 v104, v63, v63
	v_fmac_f32_e32 v105, v65, v65
	v_add_f32_e32 v104, v104, v105
	v_add_f32_e32 v103, v103, v104
	s_nop 1
	v_add_f32_dpp v103, v103, v103 quad_perm:[1,0,3,2] row_mask:0xf bank_mask:0xf
	s_nop 1
	v_add_f32_dpp v103, v103, v103 quad_perm:[2,3,0,1] row_mask:0xf bank_mask:0xf
	s_nop 1
	v_add_f32_dpp v103, v103, v103 row_half_mirror row_mask:0xf bank_mask:0xf
	s_nop 1
	v_add_f32_dpp v103, v103, v103 row_mirror row_mask:0xf bank_mask:0xf
	v_mov_b32_e32 v104, v103
	s_nop 1
	v_permlane16_swap_b32_e32 v103, v104
	s_nop 0
	v_add_f32_e32 v103, v103, v104
	v_mov_b32_e32 v104, v103
	s_nop 1
	v_permlane32_swap_b32_e32 v103, v104
	s_nop 0
	v_add_f32_e32 v103, v103, v104
	v_fma_f32 v103, v103, s37, v108
	v_rsq_f32_e32 v107, v103
	s_nop 0
	v_mul_f32_e32 v50, v50, v107
	v_mul_f32_e32 v51, v51, v107
	v_mul_f32_e32 v52, v52, v107
	v_mul_f32_e32 v53, v53, v107
	v_mul_f32_e32 v54, v54, v107
	v_mul_f32_e32 v55, v55, v107
	v_mul_f32_e32 v56, v56, v107
	v_mul_f32_e32 v57, v57, v107
	v_mul_f32_e32 v58, v58, v107
	v_mul_f32_e32 v59, v59, v107
	v_mul_f32_e32 v60, v60, v107
	v_mul_f32_e32 v61, v61, v107
	v_mul_f32_e32 v62, v62, v107
	v_mul_f32_e32 v63, v63, v107
	v_mul_f32_e32 v64, v64, v107
	v_mul_f32_e32 v65, v65, v107
	v_fma_f32 v50, v50, v66, v82
	v_fma_f32 v51, v51, v67, v83
	v_fma_f32 v52, v52, v68, v84
	v_fma_f32 v53, v53, v69, v85
	v_fma_f32 v54, v54, v70, v86
	v_fma_f32 v55, v55, v71, v87
	v_fma_f32 v56, v56, v72, v88
	v_fma_f32 v57, v57, v73, v89
	v_fma_f32 v58, v58, v74, v90
	v_fma_f32 v59, v59, v75, v91
	v_fma_f32 v60, v60, v76, v92
	v_fma_f32 v61, v61, v77, v93
	v_fma_f32 v62, v62, v78, v94
	v_fma_f32 v63, v63, v79, v95
	v_fma_f32 v64, v64, v80, v96
	v_fma_f32 v65, v65, v81, v97
	v_cvt_pk_bf16_f32 v110, v50, v51
	v_cvt_pk_bf16_f32 v111, v52, v53
	v_cvt_pk_bf16_f32 v112, v54, v55
	v_cvt_pk_bf16_f32 v113, v56, v57
	v_cvt_pk_bf16_f32 v114, v58, v59
	v_cvt_pk_bf16_f32 v115, v60, v61
	v_cvt_pk_bf16_f32 v116, v62, v63
	v_cvt_pk_bf16_f32 v117, v64, v65
	global_store_dwordx2 v101, v[110:111], s[30:31]
	global_store_dwordx2 v101, v[112:113], s[30:31] offset:512
	global_store_dwordx2 v101, v[114:115], s[30:31] offset:1024
	global_store_dwordx2 v101, v[116:117], s[30:31] offset:1536
	s_mov_b64 exec, s[0:1]
	global_store_dwordx2 v109, v[106:107], s[32:33]
	s_mov_b64 exec, -1
	s_add_u32 s30, s30, s35
	s_addc_u32 s31, s31, 0
	s_add_u32 s32, s32, s36
	s_addc_u32 s33, s33, 0
	s_waitcnt vmcnt(23)
	global_load_dwordx4 v[50:53], v100, s[28:29] nt
	global_load_dwordx4 v[54:57], v100, s[28:29] offset:1024 nt
	global_load_dwordx4 v[58:61], v100, s[28:29] offset:2048 nt
	global_load_dwordx4 v[62:65], v100, s[28:29] offset:3072 nt
	s_add_u32 s28, s28, s34
	s_addc_u32 s29, s29, 0
	v_add_f32_e32 v104, v2, v3
	v_add_f32_e32 v105, v4, v5
	v_add_f32_e32 v104, v104, v105
	v_mov_b32_e32 v102, v104
	v_add_f32_e32 v104, v6, v7
	v_add_f32_e32 v105, v8, v9
	v_add_f32_e32 v104, v104, v105
	v_add_f32_e32 v102, v102, v104
	v_add_f32_e32 v104, v10, v11
	v_add_f32_e32 v105, v12, v13
	v_add_f32_e32 v104, v104, v105
	v_add_f32_e32 v102, v102, v104
	v_add_f32_e32 v104, v14, v15
	v_add_f32_e32 v105, v16, v17
	v_add_f32_e32 v104, v104, v105
	v_add_f32_e32 v102, v102, v104
	s_nop 1
	v_add_f32_dpp v102, v102, v102 quad_perm:[1,0,3,2] row_mask:0xf bank_mask:0xf
	s_nop 1
	v_add_f32_dpp v102, v102, v102 quad_perm:[2,3,0,1] row_mask:0xf bank_mask:0xf
	s_nop 1
	v_add_f32_dpp v102, v102, v102 row_half_mirror row_mask:0xf bank_mask:0xf
	s_nop 1
	v_add_f32_dpp v102, v102, v102 row_mirror row_mask:0xf bank_mask:0xf
	v_mov_b32_e32 v104, v102
	s_nop 1
	v_permlane16_swap_b32_e32 v102, v104
	s_nop 0
	v_add_f32_e32 v102, v102, v104
	v_mov_b32_e32 v104, v102
	s_nop 1
	v_permlane32_swap_b32_e32 v102, v104
	s_nop 0
	v_add_f32_e32 v102, v102, v104
	v_mul_f32_e32 v106, 0x3a800000, v102
	v_sub_f32_e32 v2, v2, v106
	v_sub_f32_e32 v3, v3, v106
	v_sub_f32_e32 v4, v4, v106
	v_sub_f32_e32 v5, v5, v106
	v_sub_f32_e32 v6, v6, v106
	v_sub_f32_e32 v7, v7, v106
	v_sub_f32_e32 v8, v8, v106
	v_sub_f32_e32 v9, v9, v106
	v_sub_f32_e32 v10, v10, v106
	v_sub_f32_e32 v11, v11, v106
	v_sub_f32_e32 v12, v12, v106
	v_sub_f32_e32 v13, v13, v106
	v_sub_f32_e32 v14, v14, v106
	v_sub_f32_e32 v15, v15, v106
	v_sub_f32_e32 v16, v16, v106
	v_sub_f32_e32 v17, v17, v106
	v_mul_f32_e32 v104, v2, v2
	v_mul_f32_e32 v105, v4, v4
	v_fmac_f32_e32 v104, v3, v3
	v_fmac_f32_e32 v105, v5, v5
	v_add_f32_e32 v104, v104, v105
	v_mov_b32_e32 v103, v104
	v_mul_f32_e32 v104, v6, v6
	v_mul_f32_e32 v105, v8, v8
	v_fmac_f32_e32 v104, v7, v7
	v_fmac_f32_e32 v105, v9, v9
	v_add_f32_e32 v104, v104, v105
	v_add_f32_e32 v103, v103, v104
	v_mul_f32_e32 v104, v10, v10
	v_mul_f32_e32 v105, v12, v12
	v_fmac_f32_e32 v104, v11, v11
	v_fmac_f32_e32 v105, v13, v13
	v_add_f32_e32 v104, v104, v105
	v_add_f32_e32 v103, v103, v104
	v_mul_f32_e32 v104, v14, v14
	v_mul_f32_e32 v105, v16, v16
	v_fmac_f32_e32 v104, v15, v15
	v_fmac_f32_e32 v105, v17, v17
	v_add_f32_e32 v104, v104, v105
	v_add_f32_e32 v103, v103, v104
	s_nop 1
	v_add_f32_dpp v103, v103, v103 quad_perm:[1,0,3,2] row_mask:0xf bank_mask:0xf
	s_nop 1
	v_add_f32_dpp v103, v103, v103 quad_perm:[2,3,0,1] row_mask:0xf bank_mask:0xf
	s_nop 1
	v_add_f32_dpp v103, v103, v103 row_half_mirror row_mask:0xf bank_mask:0xf
	s_nop 1
	v_add_f32_dpp v103, v103, v103 row_mirror row_mask:0xf bank_mask:0xf
	v_mov_b32_e32 v104, v103
	s_nop 1
	v_permlane16_swap_b32_e32 v103, v104
	s_nop 0
	v_add_f32_e32 v103, v103, v104
	v_mov_b32_e32 v104, v103
	s_nop 1
	v_permlane32_swap_b32_e32 v103, v104
	s_nop 0
	v_add_f32_e32 v103, v103, v104
	v_fma_f32 v103, v103, s37, v108
	v_rsq_f32_e32 v107, v103
	s_nop 0
	v_mul_f32_e32 v2, v2, v107
	v_mul_f32_e32 v3, v3, v107
	v_mul_f32_e32 v4, v4, v107
	v_mul_f32_e32 v5, v5, v107
	v_mul_f32_e32 v6, v6, v107
	v_mul_f32_e32 v7, v7, v107
	v_mul_f32_e32 v8, v8, v107
	v_mul_f32_e32 v9, v9, v107
	v_mul_f32_e32 v10, v10, v107
	v_mul_f32_e32 v11, v11, v107
	v_mul_f32_e32 v12, v12, v107
	v_mul_f32_e32 v13, v13, v107
	v_mul_f32_e32 v14, v14, v107
	v_mul_f32_e32 v15, v15, v107
	v_mul_f32_e32 v16, v16, v107
	v_mul_f32_e32 v17, v17, v107
	v_fma_f32 v2, v2, v66, v82
	v_fma_f32 v3, v3, v67, v83
	v_fma_f32 v4, v4, v68, v84
	v_fma_f32 v5, v5, v69, v85
	v_fma_f32 v6, v6, v70, v86
	v_fma_f32 v7, v7, v71, v87
	v_fma_f32 v8, v8, v72, v88
	v_fma_f32 v9, v9, v73, v89
	v_fma_f32 v10, v10, v74, v90
	v_fma_f32 v11, v11, v75, v91
	v_fma_f32 v12, v12, v76, v92
	v_fma_f32 v13, v13, v77, v93
	v_fma_f32 v14, v14, v78, v94
	v_fma_f32 v15, v15, v79, v95
	v_fma_f32 v16, v16, v80, v96
	v_fma_f32 v17, v17, v81, v97
	v_cvt_pk_bf16_f32 v110, v2, v3
	v_cvt_pk_bf16_f32 v111, v4, v5
	v_cvt_pk_bf16_f32 v112, v6, v7
	v_cvt_pk_bf16_f32 v113, v8, v9
	v_cvt_pk_bf16_f32 v114, v10, v11
	v_cvt_pk_bf16_f32 v115, v12, v13
	v_cvt_pk_bf16_f32 v116, v14, v15
	v_cvt_pk_bf16_f32 v117, v16, v17
	global_store_dwordx2 v101, v[110:111], s[30:31]
	global_store_dwordx2 v101, v[112:113], s[30:31] offset:512
	global_store_dwordx2 v101, v[114:115], s[30:31] offset:1024
	global_store_dwordx2 v101, v[116:117], s[30:31] offset:1536
	s_mov_b64 exec, s[0:1]
	global_store_dwordx2 v109, v[106:107], s[32:33]
	s_mov_b64 exec, -1
	s_add_u32 s30, s30, s35
	s_addc_u32 s31, s31, 0
	s_add_u32 s32, s32, s36
	s_addc_u32 s33, s33, 0
	s_waitcnt vmcnt(23)
	global_load_dwordx4 v[2:5], v100, s[28:29] nt
	global_load_dwordx4 v[6:9], v100, s[28:29] offset:1024 nt
	global_load_dwordx4 v[10:13], v100, s[28:29] offset:2048 nt
	global_load_dwordx4 v[14:17], v100, s[28:29] offset:3072 nt
	s_add_u32 s28, s28, s34
	s_addc_u32 s29, s29, 0
	v_add_f32_e32 v104, v18, v19
	v_add_f32_e32 v105, v20, v21
	v_add_f32_e32 v104, v104, v105
	v_mov_b32_e32 v102, v104
	v_add_f32_e32 v104, v22, v23
	v_add_f32_e32 v105, v24, v25
	v_add_f32_e32 v104, v104, v105
	v_add_f32_e32 v102, v102, v104
	v_add_f32_e32 v104, v26, v27
	v_add_f32_e32 v105, v28, v29
	v_add_f32_e32 v104, v104, v105
	v_add_f32_e32 v102, v102, v104
	v_add_f32_e32 v104, v30, v31
	v_add_f32_e32 v105, v32, v33
	v_add_f32_e32 v104, v104, v105
	v_add_f32_e32 v102, v102, v104
	s_nop 1
	v_add_f32_dpp v102, v102, v102 quad_perm:[1,0,3,2] row_mask:0xf bank_mask:0xf
	s_nop 1
	v_add_f32_dpp v102, v102, v102 quad_perm:[2,3,0,1] row_mask:0xf bank_mask:0xf
	s_nop 1
	v_add_f32_dpp v102, v102, v102 row_half_mirror row_mask:0xf bank_mask:0xf
	s_nop 1
	v_add_f32_dpp v102, v102, v102 row_mirror row_mask:0xf bank_mask:0xf
	v_mov_b32_e32 v104, v102
	s_nop 1
	v_permlane16_swap_b32_e32 v102, v104
	s_nop 0
	v_add_f32_e32 v102, v102, v104
	v_mov_b32_e32 v104, v102
	s_nop 1
	v_permlane32_swap_b32_e32 v102, v104
	s_nop 0
	v_add_f32_e32 v102, v102, v104
	v_mul_f32_e32 v106, 0x3a800000, v102
	v_sub_f32_e32 v18, v18, v106
	v_sub_f32_e32 v19, v19, v106
	v_sub_f32_e32 v20, v20, v106
	v_sub_f32_e32 v21, v21, v106
	v_sub_f32_e32 v22, v22, v106
	v_sub_f32_e32 v23, v23, v106
	v_sub_f32_e32 v24, v24, v106
	v_sub_f32_e32 v25, v25, v106
	v_sub_f32_e32 v26, v26, v106
	v_sub_f32_e32 v27, v27, v106
	v_sub_f32_e32 v28, v28, v106
	v_sub_f32_e32 v29, v29, v106
	v_sub_f32_e32 v30, v30, v106
	v_sub_f32_e32 v31, v31, v106
	v_sub_f32_e32 v32, v32, v106
	v_sub_f32_e32 v33, v33, v106
	v_mul_f32_e32 v104, v18, v18
	v_mul_f32_e32 v105, v20, v20
	v_fmac_f32_e32 v104, v19, v19
	v_fmac_f32_e32 v105, v21, v21
	v_add_f32_e32 v104, v104, v105
	v_mov_b32_e32 v103, v104
	v_mul_f32_e32 v104, v22, v22
	v_mul_f32_e32 v105, v24, v24
	v_fmac_f32_e32 v104, v23, v23
	v_fmac_f32_e32 v105, v25, v25
	v_add_f32_e32 v104, v104, v105
	v_add_f32_e32 v103, v103, v104
	v_mul_f32_e32 v104, v26, v26
	v_mul_f32_e32 v105, v28, v28
	v_fmac_f32_e32 v104, v27, v27
	v_fmac_f32_e32 v105, v29, v29
	v_add_f32_e32 v104, v104, v105
	v_add_f32_e32 v103, v103, v104
	v_mul_f32_e32 v104, v30, v30
	v_mul_f32_e32 v105, v32, v32
	v_fmac_f32_e32 v104, v31, v31
	v_fmac_f32_e32 v105, v33, v33
	v_add_f32_e32 v104, v104, v105
	v_add_f32_e32 v103, v103, v104
	s_nop 1
	v_add_f32_dpp v103, v103, v103 quad_perm:[1,0,3,2] row_mask:0xf bank_mask:0xf
	s_nop 1
	v_add_f32_dpp v103, v103, v103 quad_perm:[2,3,0,1] row_mask:0xf bank_mask:0xf
	s_nop 1
	v_add_f32_dpp v103, v103, v103 row_half_mirror row_mask:0xf bank_mask:0xf
	s_nop 1
	v_add_f32_dpp v103, v103, v103 row_mirror row_mask:0xf bank_mask:0xf
	v_mov_b32_e32 v104, v103
	s_nop 1
	v_permlane16_swap_b32_e32 v103, v104
	s_nop 0
	v_add_f32_e32 v103, v103, v104
	v_mov_b32_e32 v104, v103
	s_nop 1
	v_permlane32_swap_b32_e32 v103, v104
	s_nop 0
	v_add_f32_e32 v103, v103, v104
	v_fma_f32 v103, v103, s37, v108
	v_rsq_f32_e32 v107, v103
	s_nop 0
	v_mul_f32_e32 v18, v18, v107
	v_mul_f32_e32 v19, v19, v107
	v_mul_f32_e32 v20, v20, v107
	v_mul_f32_e32 v21, v21, v107
	v_mul_f32_e32 v22, v22, v107
	v_mul_f32_e32 v23, v23, v107
	v_mul_f32_e32 v24, v24, v107
	v_mul_f32_e32 v25, v25, v107
	v_mul_f32_e32 v26, v26, v107
	v_mul_f32_e32 v27, v27, v107
	v_mul_f32_e32 v28, v28, v107
	v_mul_f32_e32 v29, v29, v107
	v_mul_f32_e32 v30, v30, v107
	v_mul_f32_e32 v31, v31, v107
	v_mul_f32_e32 v32, v32, v107
	v_mul_f32_e32 v33, v33, v107
	v_fma_f32 v18, v18, v66, v82
	v_fma_f32 v19, v19, v67, v83
	v_fma_f32 v20, v20, v68, v84
	v_fma_f32 v21, v21, v69, v85
	v_fma_f32 v22, v22, v70, v86
	v_fma_f32 v23, v23, v71, v87
	v_fma_f32 v24, v24, v72, v88
	v_fma_f32 v25, v25, v73, v89
	v_fma_f32 v26, v26, v74, v90
	v_fma_f32 v27, v27, v75, v91
	v_fma_f32 v28, v28, v76, v92
	v_fma_f32 v29, v29, v77, v93
	v_fma_f32 v30, v30, v78, v94
	v_fma_f32 v31, v31, v79, v95
	v_fma_f32 v32, v32, v80, v96
	v_fma_f32 v33, v33, v81, v97
	v_cvt_pk_bf16_f32 v110, v18, v19
	v_cvt_pk_bf16_f32 v111, v20, v21
	v_cvt_pk_bf16_f32 v112, v22, v23
	v_cvt_pk_bf16_f32 v113, v24, v25
	v_cvt_pk_bf16_f32 v114, v26, v27
	v_cvt_pk_bf16_f32 v115, v28, v29
	v_cvt_pk_bf16_f32 v116, v30, v31
	v_cvt_pk_bf16_f32 v117, v32, v33
	global_store_dwordx2 v101, v[110:111], s[30:31]
	global_store_dwordx2 v101, v[112:113], s[30:31] offset:512
	global_store_dwordx2 v101, v[114:115], s[30:31] offset:1024
	global_store_dwordx2 v101, v[116:117], s[30:31] offset:1536
	s_mov_b64 exec, s[0:1]
	global_store_dwordx2 v109, v[106:107], s[32:33]
	s_mov_b64 exec, -1
	s_add_u32 s30, s30, s35
	s_addc_u32 s31, s31, 0
	s_add_u32 s32, s32, s36
	s_addc_u32 s33, s33, 0
	s_waitcnt vmcnt(23)
	global_load_dwordx4 v[18:21], v100, s[28:29] nt
	global_load_dwordx4 v[22:25], v100, s[28:29] offset:1024 nt
	global_load_dwordx4 v[26:29], v100, s[28:29] offset:2048 nt
	global_load_dwordx4 v[30:33], v100, s[28:29] offset:3072 nt
	s_add_u32 s28, s28, s34
	s_addc_u32 s29, s29, 0
	v_add_f32_e32 v104, v34, v35
	v_add_f32_e32 v105, v36, v37
	v_add_f32_e32 v104, v104, v105
	v_mov_b32_e32 v102, v104
	v_add_f32_e32 v104, v38, v39
	v_add_f32_e32 v105, v40, v41
	v_add_f32_e32 v104, v104, v105
	v_add_f32_e32 v102, v102, v104
	v_add_f32_e32 v104, v42, v43
	v_add_f32_e32 v105, v44, v45
	v_add_f32_e32 v104, v104, v105
	v_add_f32_e32 v102, v102, v104
	v_add_f32_e32 v104, v46, v47
	v_add_f32_e32 v105, v48, v49
	v_add_f32_e32 v104, v104, v105
	v_add_f32_e32 v102, v102, v104
	s_nop 1
	v_add_f32_dpp v102, v102, v102 quad_perm:[1,0,3,2] row_mask:0xf bank_mask:0xf
	s_nop 1
	v_add_f32_dpp v102, v102, v102 quad_perm:[2,3,0,1] row_mask:0xf bank_mask:0xf
	s_nop 1
	v_add_f32_dpp v102, v102, v102 row_half_mirror row_mask:0xf bank_mask:0xf
	s_nop 1
	v_add_f32_dpp v102, v102, v102 row_mirror row_mask:0xf bank_mask:0xf
	v_mov_b32_e32 v104, v102
	s_nop 1
	v_permlane16_swap_b32_e32 v102, v104
	s_nop 0
	v_add_f32_e32 v102, v102, v104
	v_mov_b32_e32 v104, v102
	s_nop 1
	v_permlane32_swap_b32_e32 v102, v104
	s_nop 0
	v_add_f32_e32 v102, v102, v104
	v_mul_f32_e32 v106, 0x3a800000, v102
	v_sub_f32_e32 v34, v34, v106
	v_sub_f32_e32 v35, v35, v106
	v_sub_f32_e32 v36, v36, v106
	v_sub_f32_e32 v37, v37, v106
	v_sub_f32_e32 v38, v38, v106
	v_sub_f32_e32 v39, v39, v106
	v_sub_f32_e32 v40, v40, v106
	v_sub_f32_e32 v41, v41, v106
	v_sub_f32_e32 v42, v42, v106
	v_sub_f32_e32 v43, v43, v106
	v_sub_f32_e32 v44, v44, v106
	v_sub_f32_e32 v45, v45, v106
	v_sub_f32_e32 v46, v46, v106
	v_sub_f32_e32 v47, v47, v106
	v_sub_f32_e32 v48, v48, v106
	v_sub_f32_e32 v49, v49, v106
	v_mul_f32_e32 v104, v34, v34
	v_mul_f32_e32 v105, v36, v36
	v_fmac_f32_e32 v104, v35, v35
	v_fmac_f32_e32 v105, v37, v37
	v_add_f32_e32 v104, v104, v105
	v_mov_b32_e32 v103, v104
	v_mul_f32_e32 v104, v38, v38
	v_mul_f32_e32 v105, v40, v40
	v_fmac_f32_e32 v104, v39, v39
	v_fmac_f32_e32 v105, v41, v41
	v_add_f32_e32 v104, v104, v105
	v_add_f32_e32 v103, v103, v104
	v_mul_f32_e32 v104, v42, v42
	v_mul_f32_e32 v105, v44, v44
	v_fmac_f32_e32 v104, v43, v43
	v_fmac_f32_e32 v105, v45, v45
	v_add_f32_e32 v104, v104, v105
	v_add_f32_e32 v103, v103, v104
	v_mul_f32_e32 v104, v46, v46
	v_mul_f32_e32 v105, v48, v48
	v_fmac_f32_e32 v104, v47, v47
	v_fmac_f32_e32 v105, v49, v49
	v_add_f32_e32 v104, v104, v105
	v_add_f32_e32 v103, v103, v104
	s_nop 1
	v_add_f32_dpp v103, v103, v103 quad_perm:[1,0,3,2] row_mask:0xf bank_mask:0xf
	s_nop 1
	v_add_f32_dpp v103, v103, v103 quad_perm:[2,3,0,1] row_mask:0xf bank_mask:0xf
	s_nop 1
	v_add_f32_dpp v103, v103, v103 row_half_mirror row_mask:0xf bank_mask:0xf
	s_nop 1
	v_add_f32_dpp v103, v103, v103 row_mirror row_mask:0xf bank_mask:0xf
	v_mov_b32_e32 v104, v103
	s_nop 1
	v_permlane16_swap_b32_e32 v103, v104
	s_nop 0
	v_add_f32_e32 v103, v103, v104
	v_mov_b32_e32 v104, v103
	s_nop 1
	v_permlane32_swap_b32_e32 v103, v104
	s_nop 0
	v_add_f32_e32 v103, v103, v104
	v_fma_f32 v103, v103, s37, v108
	v_rsq_f32_e32 v107, v103
	s_nop 0
	v_mul_f32_e32 v34, v34, v107
	v_mul_f32_e32 v35, v35, v107
	v_mul_f32_e32 v36, v36, v107
	v_mul_f32_e32 v37, v37, v107
	v_mul_f32_e32 v38, v38, v107
	v_mul_f32_e32 v39, v39, v107
	v_mul_f32_e32 v40, v40, v107
	v_mul_f32_e32 v41, v41, v107
	v_mul_f32_e32 v42, v42, v107
	v_mul_f32_e32 v43, v43, v107
	v_mul_f32_e32 v44, v44, v107
	v_mul_f32_e32 v45, v45, v107
	v_mul_f32_e32 v46, v46, v107
	v_mul_f32_e32 v47, v47, v107
	v_mul_f32_e32 v48, v48, v107
	v_mul_f32_e32 v49, v49, v107
	v_fma_f32 v34, v34, v66, v82
	v_fma_f32 v35, v35, v67, v83
	v_fma_f32 v36, v36, v68, v84
	v_fma_f32 v37, v37, v69, v85
	v_fma_f32 v38, v38, v70, v86
	v_fma_f32 v39, v39, v71, v87
	v_fma_f32 v40, v40, v72, v88
	v_fma_f32 v41, v41, v73, v89
	v_fma_f32 v42, v42, v74, v90
	v_fma_f32 v43, v43, v75, v91
	v_fma_f32 v44, v44, v76, v92
	v_fma_f32 v45, v45, v77, v93
	v_fma_f32 v46, v46, v78, v94
	v_fma_f32 v47, v47, v79, v95
	v_fma_f32 v48, v48, v80, v96
	v_fma_f32 v49, v49, v81, v97
	v_cvt_pk_bf16_f32 v110, v34, v35
	v_cvt_pk_bf16_f32 v111, v36, v37
	v_cvt_pk_bf16_f32 v112, v38, v39
	v_cvt_pk_bf16_f32 v113, v40, v41
	v_cvt_pk_bf16_f32 v114, v42, v43
	v_cvt_pk_bf16_f32 v115, v44, v45
	v_cvt_pk_bf16_f32 v116, v46, v47
	v_cvt_pk_bf16_f32 v117, v48, v49
	global_store_dwordx2 v101, v[110:111], s[30:31]
	global_store_dwordx2 v101, v[112:113], s[30:31] offset:512
	global_store_dwordx2 v101, v[114:115], s[30:31] offset:1024
	global_store_dwordx2 v101, v[116:117], s[30:31] offset:1536
	s_mov_b64 exec, s[0:1]
	global_store_dwordx2 v109, v[106:107], s[32:33]
	s_mov_b64 exec, -1
	s_add_u32 s30, s30, s35
	s_addc_u32 s31, s31, 0
	s_add_u32 s32, s32, s36
	s_addc_u32 s33, s33, 0
	s_waitcnt vmcnt(23)
	global_load_dwordx4 v[34:37], v100, s[28:29] nt
	global_load_dwordx4 v[38:41], v100, s[28:29] offset:1024 nt
	global_load_dwordx4 v[42:45], v100, s[28:29] offset:2048 nt
	global_load_dwordx4 v[46:49], v100, s[28:29] offset:3072 nt
	s_add_u32 s28, s28, s34
	s_addc_u32 s29, s29, 0
	v_add_f32_e32 v104, v50, v51
	v_add_f32_e32 v105, v52, v53
	v_add_f32_e32 v104, v104, v105
	v_mov_b32_e32 v102, v104
	v_add_f32_e32 v104, v54, v55
	v_add_f32_e32 v105, v56, v57
	v_add_f32_e32 v104, v104, v105
	v_add_f32_e32 v102, v102, v104
	v_add_f32_e32 v104, v58, v59
	v_add_f32_e32 v105, v60, v61
	v_add_f32_e32 v104, v104, v105
	v_add_f32_e32 v102, v102, v104
	v_add_f32_e32 v104, v62, v63
	v_add_f32_e32 v105, v64, v65
	v_add_f32_e32 v104, v104, v105
	v_add_f32_e32 v102, v102, v104
	s_nop 1
	v_add_f32_dpp v102, v102, v102 quad_perm:[1,0,3,2] row_mask:0xf bank_mask:0xf
	s_nop 1
	v_add_f32_dpp v102, v102, v102 quad_perm:[2,3,0,1] row_mask:0xf bank_mask:0xf
	s_nop 1
	v_add_f32_dpp v102, v102, v102 row_half_mirror row_mask:0xf bank_mask:0xf
	s_nop 1
	v_add_f32_dpp v102, v102, v102 row_mirror row_mask:0xf bank_mask:0xf
	v_mov_b32_e32 v104, v102
	s_nop 1
	v_permlane16_swap_b32_e32 v102, v104
	s_nop 0
	v_add_f32_e32 v102, v102, v104
	v_mov_b32_e32 v104, v102
	s_nop 1
	v_permlane32_swap_b32_e32 v102, v104
	s_nop 0
	v_add_f32_e32 v102, v102, v104
	v_mul_f32_e32 v106, 0x3a800000, v102
	v_sub_f32_e32 v50, v50, v106
	v_sub_f32_e32 v51, v51, v106
	v_sub_f32_e32 v52, v52, v106
	v_sub_f32_e32 v53, v53, v106
	v_sub_f32_e32 v54, v54, v106
	v_sub_f32_e32 v55, v55, v106
	v_sub_f32_e32 v56, v56, v106
	v_sub_f32_e32 v57, v57, v106
	v_sub_f32_e32 v58, v58, v106
	v_sub_f32_e32 v59, v59, v106
	v_sub_f32_e32 v60, v60, v106
	v_sub_f32_e32 v61, v61, v106
	v_sub_f32_e32 v62, v62, v106
	v_sub_f32_e32 v63, v63, v106
	v_sub_f32_e32 v64, v64, v106
	v_sub_f32_e32 v65, v65, v106
	v_mul_f32_e32 v104, v50, v50
	v_mul_f32_e32 v105, v52, v52
	v_fmac_f32_e32 v104, v51, v51
	v_fmac_f32_e32 v105, v53, v53
	v_add_f32_e32 v104, v104, v105
	v_mov_b32_e32 v103, v104
	v_mul_f32_e32 v104, v54, v54
	v_mul_f32_e32 v105, v56, v56
	v_fmac_f32_e32 v104, v55, v55
	v_fmac_f32_e32 v105, v57, v57
	v_add_f32_e32 v104, v104, v105
	v_add_f32_e32 v103, v103, v104
	v_mul_f32_e32 v104, v58, v58
	v_mul_f32_e32 v105, v60, v60
	v_fmac_f32_e32 v104, v59, v59
	v_fmac_f32_e32 v105, v61, v61
	v_add_f32_e32 v104, v104, v105
	v_add_f32_e32 v103, v103, v104
	v_mul_f32_e32 v104, v62, v62
	v_mul_f32_e32 v105, v64, v64
	v_fmac_f32_e32 v104, v63, v63
	v_fmac_f32_e32 v105, v65, v65
	v_add_f32_e32 v104, v104, v105
	v_add_f32_e32 v103, v103, v104
	s_nop 1
	v_add_f32_dpp v103, v103, v103 quad_perm:[1,0,3,2] row_mask:0xf bank_mask:0xf
	s_nop 1
	v_add_f32_dpp v103, v103, v103 quad_perm:[2,3,0,1] row_mask:0xf bank_mask:0xf
	s_nop 1
	v_add_f32_dpp v103, v103, v103 row_half_mirror row_mask:0xf bank_mask:0xf
	s_nop 1
	v_add_f32_dpp v103, v103, v103 row_mirror row_mask:0xf bank_mask:0xf
	v_mov_b32_e32 v104, v103
	s_nop 1
	v_permlane16_swap_b32_e32 v103, v104
	s_nop 0
	v_add_f32_e32 v103, v103, v104
	v_mov_b32_e32 v104, v103
	s_nop 1
	v_permlane32_swap_b32_e32 v103, v104
	s_nop 0
	v_add_f32_e32 v103, v103, v104
	v_fma_f32 v103, v103, s37, v108
	v_rsq_f32_e32 v107, v103
	s_nop 0
	v_mul_f32_e32 v50, v50, v107
	v_mul_f32_e32 v51, v51, v107
	v_mul_f32_e32 v52, v52, v107
	v_mul_f32_e32 v53, v53, v107
	v_mul_f32_e32 v54, v54, v107
	v_mul_f32_e32 v55, v55, v107
	v_mul_f32_e32 v56, v56, v107
	v_mul_f32_e32 v57, v57, v107
	v_mul_f32_e32 v58, v58, v107
	v_mul_f32_e32 v59, v59, v107
	v_mul_f32_e32 v60, v60, v107
	v_mul_f32_e32 v61, v61, v107
	v_mul_f32_e32 v62, v62, v107
	v_mul_f32_e32 v63, v63, v107
	v_mul_f32_e32 v64, v64, v107
	v_mul_f32_e32 v65, v65, v107
	v_fma_f32 v50, v50, v66, v82
	v_fma_f32 v51, v51, v67, v83
	v_fma_f32 v52, v52, v68, v84
	v_fma_f32 v53, v53, v69, v85
	v_fma_f32 v54, v54, v70, v86
	v_fma_f32 v55, v55, v71, v87
	v_fma_f32 v56, v56, v72, v88
	v_fma_f32 v57, v57, v73, v89
	v_fma_f32 v58, v58, v74, v90
	v_fma_f32 v59, v59, v75, v91
	v_fma_f32 v60, v60, v76, v92
	v_fma_f32 v61, v61, v77, v93
	v_fma_f32 v62, v62, v78, v94
	v_fma_f32 v63, v63, v79, v95
	v_fma_f32 v64, v64, v80, v96
	v_fma_f32 v65, v65, v81, v97
	v_cvt_pk_bf16_f32 v110, v50, v51
	v_cvt_pk_bf16_f32 v111, v52, v53
	v_cvt_pk_bf16_f32 v112, v54, v55
	v_cvt_pk_bf16_f32 v113, v56, v57
	v_cvt_pk_bf16_f32 v114, v58, v59
	v_cvt_pk_bf16_f32 v115, v60, v61
	v_cvt_pk_bf16_f32 v116, v62, v63
	v_cvt_pk_bf16_f32 v117, v64, v65
	global_store_dwordx2 v101, v[110:111], s[30:31]
	global_store_dwordx2 v101, v[112:113], s[30:31] offset:512
	global_store_dwordx2 v101, v[114:115], s[30:31] offset:1024
	global_store_dwordx2 v101, v[116:117], s[30:31] offset:1536
	s_mov_b64 exec, s[0:1]
	global_store_dwordx2 v109, v[106:107], s[32:33]
	s_mov_b64 exec, -1
	s_add_u32 s30, s30, s35
	s_addc_u32 s31, s31, 0
	s_add_u32 s32, s32, s36
	s_addc_u32 s33, s33, 0
	s_waitcnt vmcnt(23)
	global_load_dwordx4 v[50:53], v100, s[28:29] nt
	global_load_dwordx4 v[54:57], v100, s[28:29] offset:1024 nt
	global_load_dwordx4 v[58:61], v100, s[28:29] offset:2048 nt
	global_load_dwordx4 v[62:65], v100, s[28:29] offset:3072 nt
	s_add_u32 s28, s28, s34
	s_addc_u32 s29, s29, 0
	v_add_f32_e32 v104, v2, v3
	v_add_f32_e32 v105, v4, v5
	v_add_f32_e32 v104, v104, v105
	v_mov_b32_e32 v102, v104
	v_add_f32_e32 v104, v6, v7
	v_add_f32_e32 v105, v8, v9
	v_add_f32_e32 v104, v104, v105
	v_add_f32_e32 v102, v102, v104
	v_add_f32_e32 v104, v10, v11
	v_add_f32_e32 v105, v12, v13
	v_add_f32_e32 v104, v104, v105
	v_add_f32_e32 v102, v102, v104
	v_add_f32_e32 v104, v14, v15
	v_add_f32_e32 v105, v16, v17
	v_add_f32_e32 v104, v104, v105
	v_add_f32_e32 v102, v102, v104
	s_nop 1
	v_add_f32_dpp v102, v102, v102 quad_perm:[1,0,3,2] row_mask:0xf bank_mask:0xf
	s_nop 1
	v_add_f32_dpp v102, v102, v102 quad_perm:[2,3,0,1] row_mask:0xf bank_mask:0xf
	s_nop 1
	v_add_f32_dpp v102, v102, v102 row_half_mirror row_mask:0xf bank_mask:0xf
	s_nop 1
	v_add_f32_dpp v102, v102, v102 row_mirror row_mask:0xf bank_mask:0xf
	v_mov_b32_e32 v104, v102
	s_nop 1
	v_permlane16_swap_b32_e32 v102, v104
	s_nop 0
	v_add_f32_e32 v102, v102, v104
	v_mov_b32_e32 v104, v102
	s_nop 1
	v_permlane32_swap_b32_e32 v102, v104
	s_nop 0
	v_add_f32_e32 v102, v102, v104
	v_mul_f32_e32 v106, 0x3a800000, v102
	v_sub_f32_e32 v2, v2, v106
	v_sub_f32_e32 v3, v3, v106
	v_sub_f32_e32 v4, v4, v106
	v_sub_f32_e32 v5, v5, v106
	v_sub_f32_e32 v6, v6, v106
	v_sub_f32_e32 v7, v7, v106
	v_sub_f32_e32 v8, v8, v106
	v_sub_f32_e32 v9, v9, v106
	v_sub_f32_e32 v10, v10, v106
	v_sub_f32_e32 v11, v11, v106
	v_sub_f32_e32 v12, v12, v106
	v_sub_f32_e32 v13, v13, v106
	v_sub_f32_e32 v14, v14, v106
	v_sub_f32_e32 v15, v15, v106
	v_sub_f32_e32 v16, v16, v106
	v_sub_f32_e32 v17, v17, v106
	v_mul_f32_e32 v104, v2, v2
	v_mul_f32_e32 v105, v4, v4
	v_fmac_f32_e32 v104, v3, v3
	v_fmac_f32_e32 v105, v5, v5
	v_add_f32_e32 v104, v104, v105
	v_mov_b32_e32 v103, v104
	v_mul_f32_e32 v104, v6, v6
	v_mul_f32_e32 v105, v8, v8
	v_fmac_f32_e32 v104, v7, v7
	v_fmac_f32_e32 v105, v9, v9
	v_add_f32_e32 v104, v104, v105
	v_add_f32_e32 v103, v103, v104
	v_mul_f32_e32 v104, v10, v10
	v_mul_f32_e32 v105, v12, v12
	v_fmac_f32_e32 v104, v11, v11
	v_fmac_f32_e32 v105, v13, v13
	v_add_f32_e32 v104, v104, v105
	v_add_f32_e32 v103, v103, v104
	v_mul_f32_e32 v104, v14, v14
	v_mul_f32_e32 v105, v16, v16
	v_fmac_f32_e32 v104, v15, v15
	v_fmac_f32_e32 v105, v17, v17
	v_add_f32_e32 v104, v104, v105
	v_add_f32_e32 v103, v103, v104
	s_nop 1
	v_add_f32_dpp v103, v103, v103 quad_perm:[1,0,3,2] row_mask:0xf bank_mask:0xf
	s_nop 1
	v_add_f32_dpp v103, v103, v103 quad_perm:[2,3,0,1] row_mask:0xf bank_mask:0xf
	s_nop 1
	v_add_f32_dpp v103, v103, v103 row_half_mirror row_mask:0xf bank_mask:0xf
	s_nop 1
	v_add_f32_dpp v103, v103, v103 row_mirror row_mask:0xf bank_mask:0xf
	v_mov_b32_e32 v104, v103
	s_nop 1
	v_permlane16_swap_b32_e32 v103, v104
	s_nop 0
	v_add_f32_e32 v103, v103, v104
	v_mov_b32_e32 v104, v103
	s_nop 1
	v_permlane32_swap_b32_e32 v103, v104
	s_nop 0
	v_add_f32_e32 v103, v103, v104
	v_fma_f32 v103, v103, s37, v108
	v_rsq_f32_e32 v107, v103
	s_nop 0
	v_mul_f32_e32 v2, v2, v107
	v_mul_f32_e32 v3, v3, v107
	v_mul_f32_e32 v4, v4, v107
	v_mul_f32_e32 v5, v5, v107
	v_mul_f32_e32 v6, v6, v107
	v_mul_f32_e32 v7, v7, v107
	v_mul_f32_e32 v8, v8, v107
	v_mul_f32_e32 v9, v9, v107
	v_mul_f32_e32 v10, v10, v107
	v_mul_f32_e32 v11, v11, v107
	v_mul_f32_e32 v12, v12, v107
	v_mul_f32_e32 v13, v13, v107
	v_mul_f32_e32 v14, v14, v107
	v_mul_f32_e32 v15, v15, v107
	v_mul_f32_e32 v16, v16, v107
	v_mul_f32_e32 v17, v17, v107
	v_fma_f32 v2, v2, v66, v82
	v_fma_f32 v3, v3, v67, v83
	v_fma_f32 v4, v4, v68, v84
	v_fma_f32 v5, v5, v69, v85
	v_fma_f32 v6, v6, v70, v86
	v_fma_f32 v7, v7, v71, v87
	v_fma_f32 v8, v8, v72, v88
	v_fma_f32 v9, v9, v73, v89
	v_fma_f32 v10, v10, v74, v90
	v_fma_f32 v11, v11, v75, v91
	v_fma_f32 v12, v12, v76, v92
	v_fma_f32 v13, v13, v77, v93
	v_fma_f32 v14, v14, v78, v94
	v_fma_f32 v15, v15, v79, v95
	v_fma_f32 v16, v16, v80, v96
	v_fma_f32 v17, v17, v81, v97
	v_cvt_pk_bf16_f32 v110, v2, v3
	v_cvt_pk_bf16_f32 v111, v4, v5
	v_cvt_pk_bf16_f32 v112, v6, v7
	v_cvt_pk_bf16_f32 v113, v8, v9
	v_cvt_pk_bf16_f32 v114, v10, v11
	v_cvt_pk_bf16_f32 v115, v12, v13
	v_cvt_pk_bf16_f32 v116, v14, v15
	v_cvt_pk_bf16_f32 v117, v16, v17
	global_store_dwordx2 v101, v[110:111], s[30:31]
	global_store_dwordx2 v101, v[112:113], s[30:31] offset:512
	global_store_dwordx2 v101, v[114:115], s[30:31] offset:1024
	global_store_dwordx2 v101, v[116:117], s[30:31] offset:1536
	s_mov_b64 exec, s[0:1]
	global_store_dwordx2 v109, v[106:107], s[32:33]
	s_mov_b64 exec, -1
	s_add_u32 s30, s30, s35
	s_addc_u32 s31, s31, 0
	s_add_u32 s32, s32, s36
	s_addc_u32 s33, s33, 0
	s_waitcnt vmcnt(23)
	v_add_f32_e32 v104, v18, v19
	v_add_f32_e32 v105, v20, v21
	v_add_f32_e32 v104, v104, v105
	v_mov_b32_e32 v102, v104
	v_add_f32_e32 v104, v22, v23
	v_add_f32_e32 v105, v24, v25
	v_add_f32_e32 v104, v104, v105
	v_add_f32_e32 v102, v102, v104
	v_add_f32_e32 v104, v26, v27
	v_add_f32_e32 v105, v28, v29
	v_add_f32_e32 v104, v104, v105
	v_add_f32_e32 v102, v102, v104
	v_add_f32_e32 v104, v30, v31
	v_add_f32_e32 v105, v32, v33
	v_add_f32_e32 v104, v104, v105
	v_add_f32_e32 v102, v102, v104
	s_nop 1
	v_add_f32_dpp v102, v102, v102 quad_perm:[1,0,3,2] row_mask:0xf bank_mask:0xf
	s_nop 1
	v_add_f32_dpp v102, v102, v102 quad_perm:[2,3,0,1] row_mask:0xf bank_mask:0xf
	s_nop 1
	v_add_f32_dpp v102, v102, v102 row_half_mirror row_mask:0xf bank_mask:0xf
	s_nop 1
	v_add_f32_dpp v102, v102, v102 row_mirror row_mask:0xf bank_mask:0xf
	v_mov_b32_e32 v104, v102
	s_nop 1
	v_permlane16_swap_b32_e32 v102, v104
	s_nop 0
	v_add_f32_e32 v102, v102, v104
	v_mov_b32_e32 v104, v102
	s_nop 1
	v_permlane32_swap_b32_e32 v102, v104
	s_nop 0
	v_add_f32_e32 v102, v102, v104
	v_mul_f32_e32 v106, 0x3a800000, v102
	v_sub_f32_e32 v18, v18, v106
	v_sub_f32_e32 v19, v19, v106
	v_sub_f32_e32 v20, v20, v106
	v_sub_f32_e32 v21, v21, v106
	v_sub_f32_e32 v22, v22, v106
	v_sub_f32_e32 v23, v23, v106
	v_sub_f32_e32 v24, v24, v106
	v_sub_f32_e32 v25, v25, v106
	v_sub_f32_e32 v26, v26, v106
	v_sub_f32_e32 v27, v27, v106
	v_sub_f32_e32 v28, v28, v106
	v_sub_f32_e32 v29, v29, v106
	v_sub_f32_e32 v30, v30, v106
	v_sub_f32_e32 v31, v31, v106
	v_sub_f32_e32 v32, v32, v106
	v_sub_f32_e32 v33, v33, v106
	v_mul_f32_e32 v104, v18, v18
	v_mul_f32_e32 v105, v20, v20
	v_fmac_f32_e32 v104, v19, v19
	v_fmac_f32_e32 v105, v21, v21
	v_add_f32_e32 v104, v104, v105
	v_mov_b32_e32 v103, v104
	v_mul_f32_e32 v104, v22, v22
	v_mul_f32_e32 v105, v24, v24
	v_fmac_f32_e32 v104, v23, v23
	v_fmac_f32_e32 v105, v25, v25
	v_add_f32_e32 v104, v104, v105
	v_add_f32_e32 v103, v103, v104
	v_mul_f32_e32 v104, v26, v26
	v_mul_f32_e32 v105, v28, v28
	v_fmac_f32_e32 v104, v27, v27
	v_fmac_f32_e32 v105, v29, v29
	v_add_f32_e32 v104, v104, v105
	v_add_f32_e32 v103, v103, v104
	v_mul_f32_e32 v104, v30, v30
	v_mul_f32_e32 v105, v32, v32
	v_fmac_f32_e32 v104, v31, v31
	v_fmac_f32_e32 v105, v33, v33
	v_add_f32_e32 v104, v104, v105
	v_add_f32_e32 v103, v103, v104
	s_nop 1
	v_add_f32_dpp v103, v103, v103 quad_perm:[1,0,3,2] row_mask:0xf bank_mask:0xf
	s_nop 1
	v_add_f32_dpp v103, v103, v103 quad_perm:[2,3,0,1] row_mask:0xf bank_mask:0xf
	s_nop 1
	v_add_f32_dpp v103, v103, v103 row_half_mirror row_mask:0xf bank_mask:0xf
	s_nop 1
	v_add_f32_dpp v103, v103, v103 row_mirror row_mask:0xf bank_mask:0xf
	v_mov_b32_e32 v104, v103
	s_nop 1
	v_permlane16_swap_b32_e32 v103, v104
	s_nop 0
	v_add_f32_e32 v103, v103, v104
	v_mov_b32_e32 v104, v103
	s_nop 1
	v_permlane32_swap_b32_e32 v103, v104
	s_nop 0
	v_add_f32_e32 v103, v103, v104
	v_fma_f32 v103, v103, s37, v108
	v_rsq_f32_e32 v107, v103
	s_nop 0
	v_mul_f32_e32 v18, v18, v107
	v_mul_f32_e32 v19, v19, v107
	v_mul_f32_e32 v20, v20, v107
	v_mul_f32_e32 v21, v21, v107
	v_mul_f32_e32 v22, v22, v107
	v_mul_f32_e32 v23, v23, v107
	v_mul_f32_e32 v24, v24, v107
	v_mul_f32_e32 v25, v25, v107
	v_mul_f32_e32 v26, v26, v107
	v_mul_f32_e32 v27, v27, v107
	v_mul_f32_e32 v28, v28, v107
	v_mul_f32_e32 v29, v29, v107
	v_mul_f32_e32 v30, v30, v107
	v_mul_f32_e32 v31, v31, v107
	v_mul_f32_e32 v32, v32, v107
	v_mul_f32_e32 v33, v33, v107
	v_fma_f32 v18, v18, v66, v82
	v_fma_f32 v19, v19, v67, v83
	v_fma_f32 v20, v20, v68, v84
	v_fma_f32 v21, v21, v69, v85
	v_fma_f32 v22, v22, v70, v86
	v_fma_f32 v23, v23, v71, v87
	v_fma_f32 v24, v24, v72, v88
	v_fma_f32 v25, v25, v73, v89
	v_fma_f32 v26, v26, v74, v90
	v_fma_f32 v27, v27, v75, v91
	v_fma_f32 v28, v28, v76, v92
	v_fma_f32 v29, v29, v77, v93
	v_fma_f32 v30, v30, v78, v94
	v_fma_f32 v31, v31, v79, v95
	v_fma_f32 v32, v32, v80, v96
	v_fma_f32 v33, v33, v81, v97
	v_cvt_pk_bf16_f32 v110, v18, v19
	v_cvt_pk_bf16_f32 v111, v20, v21
	v_cvt_pk_bf16_f32 v112, v22, v23
	v_cvt_pk_bf16_f32 v113, v24, v25
	v_cvt_pk_bf16_f32 v114, v26, v27
	v_cvt_pk_bf16_f32 v115, v28, v29
	v_cvt_pk_bf16_f32 v116, v30, v31
	v_cvt_pk_bf16_f32 v117, v32, v33
	global_store_dwordx2 v101, v[110:111], s[30:31]
	global_store_dwordx2 v101, v[112:113], s[30:31] offset:512
	global_store_dwordx2 v101, v[114:115], s[30:31] offset:1024
	global_store_dwordx2 v101, v[116:117], s[30:31] offset:1536
	s_mov_b64 exec, s[0:1]
	global_store_dwordx2 v109, v[106:107], s[32:33]
	s_mov_b64 exec, -1
	s_add_u32 s30, s30, s35
	s_addc_u32 s31, s31, 0
	s_add_u32 s32, s32, s36
	s_addc_u32 s33, s33, 0
	s_waitcnt vmcnt(19)
	v_add_f32_e32 v104, v34, v35
	v_add_f32_e32 v105, v36, v37
	v_add_f32_e32 v104, v104, v105
	v_mov_b32_e32 v102, v104
	v_add_f32_e32 v104, v38, v39
	v_add_f32_e32 v105, v40, v41
	v_add_f32_e32 v104, v104, v105
	v_add_f32_e32 v102, v102, v104
	v_add_f32_e32 v104, v42, v43
	v_add_f32_e32 v105, v44, v45
	v_add_f32_e32 v104, v104, v105
	v_add_f32_e32 v102, v102, v104
	v_add_f32_e32 v104, v46, v47
	v_add_f32_e32 v105, v48, v49
	v_add_f32_e32 v104, v104, v105
	v_add_f32_e32 v102, v102, v104
	s_nop 1
	v_add_f32_dpp v102, v102, v102 quad_perm:[1,0,3,2] row_mask:0xf bank_mask:0xf
	s_nop 1
	v_add_f32_dpp v102, v102, v102 quad_perm:[2,3,0,1] row_mask:0xf bank_mask:0xf
	s_nop 1
	v_add_f32_dpp v102, v102, v102 row_half_mirror row_mask:0xf bank_mask:0xf
	s_nop 1
	v_add_f32_dpp v102, v102, v102 row_mirror row_mask:0xf bank_mask:0xf
	v_mov_b32_e32 v104, v102
	s_nop 1
	v_permlane16_swap_b32_e32 v102, v104
	s_nop 0
	v_add_f32_e32 v102, v102, v104
	v_mov_b32_e32 v104, v102
	s_nop 1
	v_permlane32_swap_b32_e32 v102, v104
	s_nop 0
	v_add_f32_e32 v102, v102, v104
	v_mul_f32_e32 v106, 0x3a800000, v102
	v_sub_f32_e32 v34, v34, v106
	v_sub_f32_e32 v35, v35, v106
	v_sub_f32_e32 v36, v36, v106
	v_sub_f32_e32 v37, v37, v106
	v_sub_f32_e32 v38, v38, v106
	v_sub_f32_e32 v39, v39, v106
	v_sub_f32_e32 v40, v40, v106
	v_sub_f32_e32 v41, v41, v106
	v_sub_f32_e32 v42, v42, v106
	v_sub_f32_e32 v43, v43, v106
	v_sub_f32_e32 v44, v44, v106
	v_sub_f32_e32 v45, v45, v106
	v_sub_f32_e32 v46, v46, v106
	v_sub_f32_e32 v47, v47, v106
	v_sub_f32_e32 v48, v48, v106
	v_sub_f32_e32 v49, v49, v106
	v_mul_f32_e32 v104, v34, v34
	v_mul_f32_e32 v105, v36, v36
	v_fmac_f32_e32 v104, v35, v35
	v_fmac_f32_e32 v105, v37, v37
	v_add_f32_e32 v104, v104, v105
	v_mov_b32_e32 v103, v104
	v_mul_f32_e32 v104, v38, v38
	v_mul_f32_e32 v105, v40, v40
	v_fmac_f32_e32 v104, v39, v39
	v_fmac_f32_e32 v105, v41, v41
	v_add_f32_e32 v104, v104, v105
	v_add_f32_e32 v103, v103, v104
	v_mul_f32_e32 v104, v42, v42
	v_mul_f32_e32 v105, v44, v44
	v_fmac_f32_e32 v104, v43, v43
	v_fmac_f32_e32 v105, v45, v45
	v_add_f32_e32 v104, v104, v105
	v_add_f32_e32 v103, v103, v104
	v_mul_f32_e32 v104, v46, v46
	v_mul_f32_e32 v105, v48, v48
	v_fmac_f32_e32 v104, v47, v47
	v_fmac_f32_e32 v105, v49, v49
	v_add_f32_e32 v104, v104, v105
	v_add_f32_e32 v103, v103, v104
	s_nop 1
	v_add_f32_dpp v103, v103, v103 quad_perm:[1,0,3,2] row_mask:0xf bank_mask:0xf
	s_nop 1
	v_add_f32_dpp v103, v103, v103 quad_perm:[2,3,0,1] row_mask:0xf bank_mask:0xf
	s_nop 1
	v_add_f32_dpp v103, v103, v103 row_half_mirror row_mask:0xf bank_mask:0xf
	s_nop 1
	v_add_f32_dpp v103, v103, v103 row_mirror row_mask:0xf bank_mask:0xf
	v_mov_b32_e32 v104, v103
	s_nop 1
	v_permlane16_swap_b32_e32 v103, v104
	s_nop 0
	v_add_f32_e32 v103, v103, v104
	v_mov_b32_e32 v104, v103
	s_nop 1
	v_permlane32_swap_b32_e32 v103, v104
	s_nop 0
	v_add_f32_e32 v103, v103, v104
	v_fma_f32 v103, v103, s37, v108
	v_rsq_f32_e32 v107, v103
	s_nop 0
	v_mul_f32_e32 v34, v34, v107
	v_mul_f32_e32 v35, v35, v107
	v_mul_f32_e32 v36, v36, v107
	v_mul_f32_e32 v37, v37, v107
	v_mul_f32_e32 v38, v38, v107
	v_mul_f32_e32 v39, v39, v107
	v_mul_f32_e32 v40, v40, v107
	v_mul_f32_e32 v41, v41, v107
	v_mul_f32_e32 v42, v42, v107
	v_mul_f32_e32 v43, v43, v107
	v_mul_f32_e32 v44, v44, v107
	v_mul_f32_e32 v45, v45, v107
	v_mul_f32_e32 v46, v46, v107
	v_mul_f32_e32 v47, v47, v107
	v_mul_f32_e32 v48, v48, v107
	v_mul_f32_e32 v49, v49, v107
	v_fma_f32 v34, v34, v66, v82
	v_fma_f32 v35, v35, v67, v83
	v_fma_f32 v36, v36, v68, v84
	v_fma_f32 v37, v37, v69, v85
	v_fma_f32 v38, v38, v70, v86
	v_fma_f32 v39, v39, v71, v87
	v_fma_f32 v40, v40, v72, v88
	v_fma_f32 v41, v41, v73, v89
	v_fma_f32 v42, v42, v74, v90
	v_fma_f32 v43, v43, v75, v91
	v_fma_f32 v44, v44, v76, v92
	v_fma_f32 v45, v45, v77, v93
	v_fma_f32 v46, v46, v78, v94
	v_fma_f32 v47, v47, v79, v95
	v_fma_f32 v48, v48, v80, v96
	v_fma_f32 v49, v49, v81, v97
	v_cvt_pk_bf16_f32 v110, v34, v35
	v_cvt_pk_bf16_f32 v111, v36, v37
	v_cvt_pk_bf16_f32 v112, v38, v39
	v_cvt_pk_bf16_f32 v113, v40, v41
	v_cvt_pk_bf16_f32 v114, v42, v43
	v_cvt_pk_bf16_f32 v115, v44, v45
	v_cvt_pk_bf16_f32 v116, v46, v47
	v_cvt_pk_bf16_f32 v117, v48, v49
	global_store_dwordx2 v101, v[110:111], s[30:31]
	global_store_dwordx2 v101, v[112:113], s[30:31] offset:512
	global_store_dwordx2 v101, v[114:115], s[30:31] offset:1024
	global_store_dwordx2 v101, v[116:117], s[30:31] offset:1536
	s_mov_b64 exec, s[0:1]
	global_store_dwordx2 v109, v[106:107], s[32:33]
	s_mov_b64 exec, -1
	s_add_u32 s30, s30, s35
	s_addc_u32 s31, s31, 0
	s_add_u32 s32, s32, s36
	s_addc_u32 s33, s33, 0
	s_waitcnt vmcnt(15)
	v_add_f32_e32 v104, v50, v51
	v_add_f32_e32 v105, v52, v53
	v_add_f32_e32 v104, v104, v105
	v_mov_b32_e32 v102, v104
	v_add_f32_e32 v104, v54, v55
	v_add_f32_e32 v105, v56, v57
	v_add_f32_e32 v104, v104, v105
	v_add_f32_e32 v102, v102, v104
	v_add_f32_e32 v104, v58, v59
	v_add_f32_e32 v105, v60, v61
	v_add_f32_e32 v104, v104, v105
	v_add_f32_e32 v102, v102, v104
	v_add_f32_e32 v104, v62, v63
	v_add_f32_e32 v105, v64, v65
	v_add_f32_e32 v104, v104, v105
	v_add_f32_e32 v102, v102, v104
	s_nop 1
	v_add_f32_dpp v102, v102, v102 quad_perm:[1,0,3,2] row_mask:0xf bank_mask:0xf
	s_nop 1
	v_add_f32_dpp v102, v102, v102 quad_perm:[2,3,0,1] row_mask:0xf bank_mask:0xf
	s_nop 1
	v_add_f32_dpp v102, v102, v102 row_half_mirror row_mask:0xf bank_mask:0xf
	s_nop 1
	v_add_f32_dpp v102, v102, v102 row_mirror row_mask:0xf bank_mask:0xf
	v_mov_b32_e32 v104, v102
	s_nop 1
	v_permlane16_swap_b32_e32 v102, v104
	s_nop 0
	v_add_f32_e32 v102, v102, v104
	v_mov_b32_e32 v104, v102
	s_nop 1
	v_permlane32_swap_b32_e32 v102, v104
	s_nop 0
	v_add_f32_e32 v102, v102, v104
	v_mul_f32_e32 v106, 0x3a800000, v102
	v_sub_f32_e32 v50, v50, v106
	v_sub_f32_e32 v51, v51, v106
	v_sub_f32_e32 v52, v52, v106
	v_sub_f32_e32 v53, v53, v106
	v_sub_f32_e32 v54, v54, v106
	v_sub_f32_e32 v55, v55, v106
	v_sub_f32_e32 v56, v56, v106
	v_sub_f32_e32 v57, v57, v106
	v_sub_f32_e32 v58, v58, v106
	v_sub_f32_e32 v59, v59, v106
	v_sub_f32_e32 v60, v60, v106
	v_sub_f32_e32 v61, v61, v106
	v_sub_f32_e32 v62, v62, v106
	v_sub_f32_e32 v63, v63, v106
	v_sub_f32_e32 v64, v64, v106
	v_sub_f32_e32 v65, v65, v106
	v_mul_f32_e32 v104, v50, v50
	v_mul_f32_e32 v105, v52, v52
	v_fmac_f32_e32 v104, v51, v51
	v_fmac_f32_e32 v105, v53, v53
	v_add_f32_e32 v104, v104, v105
	v_mov_b32_e32 v103, v104
	v_mul_f32_e32 v104, v54, v54
	v_mul_f32_e32 v105, v56, v56
	v_fmac_f32_e32 v104, v55, v55
	v_fmac_f32_e32 v105, v57, v57
	v_add_f32_e32 v104, v104, v105
	v_add_f32_e32 v103, v103, v104
	v_mul_f32_e32 v104, v58, v58
	v_mul_f32_e32 v105, v60, v60
	v_fmac_f32_e32 v104, v59, v59
	v_fmac_f32_e32 v105, v61, v61
	v_add_f32_e32 v104, v104, v105
	v_add_f32_e32 v103, v103, v104
	v_mul_f32_e32 v104, v62, v62
	v_mul_f32_e32 v105, v64, v64
	v_fmac_f32_e32 v104, v63, v63
	v_fmac_f32_e32 v105, v65, v65
	v_add_f32_e32 v104, v104, v105
	v_add_f32_e32 v103, v103, v104
	s_nop 1
	v_add_f32_dpp v103, v103, v103 quad_perm:[1,0,3,2] row_mask:0xf bank_mask:0xf
	s_nop 1
	v_add_f32_dpp v103, v103, v103 quad_perm:[2,3,0,1] row_mask:0xf bank_mask:0xf
	s_nop 1
	v_add_f32_dpp v103, v103, v103 row_half_mirror row_mask:0xf bank_mask:0xf
	s_nop 1
	v_add_f32_dpp v103, v103, v103 row_mirror row_mask:0xf bank_mask:0xf
	v_mov_b32_e32 v104, v103
	s_nop 1
	v_permlane16_swap_b32_e32 v103, v104
	s_nop 0
	v_add_f32_e32 v103, v103, v104
	v_mov_b32_e32 v104, v103
	s_nop 1
	v_permlane32_swap_b32_e32 v103, v104
	s_nop 0
	v_add_f32_e32 v103, v103, v104
	v_fma_f32 v103, v103, s37, v108
	v_rsq_f32_e32 v107, v103
	s_nop 0
	v_mul_f32_e32 v50, v50, v107
	v_mul_f32_e32 v51, v51, v107
	v_mul_f32_e32 v52, v52, v107
	v_mul_f32_e32 v53, v53, v107
	v_mul_f32_e32 v54, v54, v107
	v_mul_f32_e32 v55, v55, v107
	v_mul_f32_e32 v56, v56, v107
	v_mul_f32_e32 v57, v57, v107
	v_mul_f32_e32 v58, v58, v107
	v_mul_f32_e32 v59, v59, v107
	v_mul_f32_e32 v60, v60, v107
	v_mul_f32_e32 v61, v61, v107
	v_mul_f32_e32 v62, v62, v107
	v_mul_f32_e32 v63, v63, v107
	v_mul_f32_e32 v64, v64, v107
	v_mul_f32_e32 v65, v65, v107
	v_fma_f32 v50, v50, v66, v82
	v_fma_f32 v51, v51, v67, v83
	v_fma_f32 v52, v52, v68, v84
	v_fma_f32 v53, v53, v69, v85
	v_fma_f32 v54, v54, v70, v86
	v_fma_f32 v55, v55, v71, v87
	v_fma_f32 v56, v56, v72, v88
	v_fma_f32 v57, v57, v73, v89
	v_fma_f32 v58, v58, v74, v90
	v_fma_f32 v59, v59, v75, v91
	v_fma_f32 v60, v60, v76, v92
	v_fma_f32 v61, v61, v77, v93
	v_fma_f32 v62, v62, v78, v94
	v_fma_f32 v63, v63, v79, v95
	v_fma_f32 v64, v64, v80, v96
	v_fma_f32 v65, v65, v81, v97
	v_cvt_pk_bf16_f32 v110, v50, v51
	v_cvt_pk_bf16_f32 v111, v52, v53
	v_cvt_pk_bf16_f32 v112, v54, v55
	v_cvt_pk_bf16_f32 v113, v56, v57
	v_cvt_pk_bf16_f32 v114, v58, v59
	v_cvt_pk_bf16_f32 v115, v60, v61
	v_cvt_pk_bf16_f32 v116, v62, v63
	v_cvt_pk_bf16_f32 v117, v64, v65
	global_store_dwordx2 v101, v[110:111], s[30:31]
	global_store_dwordx2 v101, v[112:113], s[30:31] offset:512
	global_store_dwordx2 v101, v[114:115], s[30:31] offset:1024
	global_store_dwordx2 v101, v[116:117], s[30:31] offset:1536
	s_mov_b64 exec, s[0:1]
	global_store_dwordx2 v109, v[106:107], s[32:33]
	s_mov_b64 exec, -1
	s_add_u32 s30, s30, s35
	s_addc_u32 s31, s31, 0
	s_add_u32 s32, s32, s36
	s_addc_u32 s33, s33, 0
	s_cmp_lt_u32 s4, 16
	s_cbranch_scc0 .Lln0_done
	v_readlane_b32 s6, v240, 6
	v_readlane_b32 s7, v240, 7
	s_lshl_b32 s38, s4, 12
	s_add_u32 s28, s6, s38
	s_addc_u32 s29, s7, 0
	s_add_i32 s39, s4, 0x8000
	s_lshl_b32 s38, s39, 11
	s_add_u32 s38, s38, 0x2400000
	s_add_u32 s30, s94, s38
	s_addc_u32 s31, s95, 0
	s_lshl_b32 s38, s39, 3
	s_add_u32 s32, s94, s38
	s_addc_u32 s33, s95, 0
	s_nop 1
	global_load_dwordx4 v[2:5], v100, s[28:29] nt
	global_load_dwordx4 v[6:9], v100, s[28:29] offset:1024 nt
	global_load_dwordx4 v[10:13], v100, s[28:29] offset:2048 nt
	global_load_dwordx4 v[14:17], v100, s[28:29] offset:3072 nt
	s_waitcnt vmcnt(0)
	v_add_f32_e32 v104, v2, v3
	v_add_f32_e32 v105, v4, v5
	v_add_f32_e32 v104, v104, v105
	v_mov_b32_e32 v102, v104
	v_add_f32_e32 v104, v6, v7
	v_add_f32_e32 v105, v8, v9
	v_add_f32_e32 v104, v104, v105
	v_add_f32_e32 v102, v102, v104
	v_add_f32_e32 v104, v10, v11
	v_add_f32_e32 v105, v12, v13
	v_add_f32_e32 v104, v104, v105
	v_add_f32_e32 v102, v102, v104
	v_add_f32_e32 v104, v14, v15
	v_add_f32_e32 v105, v16, v17
	v_add_f32_e32 v104, v104, v105
	v_add_f32_e32 v102, v102, v104
	s_nop 1
	v_add_f32_dpp v102, v102, v102 quad_perm:[1,0,3,2] row_mask:0xf bank_mask:0xf
	s_nop 1
	v_add_f32_dpp v102, v102, v102 quad_perm:[2,3,0,1] row_mask:0xf bank_mask:0xf
	s_nop 1
	v_add_f32_dpp v102, v102, v102 row_half_mirror row_mask:0xf bank_mask:0xf
	s_nop 1
	v_add_f32_dpp v102, v102, v102 row_mirror row_mask:0xf bank_mask:0xf
	v_mov_b32_e32 v104, v102
	s_nop 1
	v_permlane16_swap_b32_e32 v102, v104
	s_nop 0
	v_add_f32_e32 v102, v102, v104
	v_mov_b32_e32 v104, v102
	s_nop 1
	v_permlane32_swap_b32_e32 v102, v104
	s_nop 0
	v_add_f32_e32 v102, v102, v104
	v_mul_f32_e32 v106, 0x3a800000, v102
	v_sub_f32_e32 v2, v2, v106
	v_sub_f32_e32 v3, v3, v106
	v_sub_f32_e32 v4, v4, v106
	v_sub_f32_e32 v5, v5, v106
	v_sub_f32_e32 v6, v6, v106
	v_sub_f32_e32 v7, v7, v106
	v_sub_f32_e32 v8, v8, v106
	v_sub_f32_e32 v9, v9, v106
	v_sub_f32_e32 v10, v10, v106
	v_sub_f32_e32 v11, v11, v106
	v_sub_f32_e32 v12, v12, v106
	v_sub_f32_e32 v13, v13, v106
	v_sub_f32_e32 v14, v14, v106
	v_sub_f32_e32 v15, v15, v106
	v_sub_f32_e32 v16, v16, v106
	v_sub_f32_e32 v17, v17, v106
	v_mul_f32_e32 v104, v2, v2
	v_mul_f32_e32 v105, v4, v4
	v_fmac_f32_e32 v104, v3, v3
	v_fmac_f32_e32 v105, v5, v5
	v_add_f32_e32 v104, v104, v105
	v_mov_b32_e32 v103, v104
	v_mul_f32_e32 v104, v6, v6
	v_mul_f32_e32 v105, v8, v8
	v_fmac_f32_e32 v104, v7, v7
	v_fmac_f32_e32 v105, v9, v9
	v_add_f32_e32 v104, v104, v105
	v_add_f32_e32 v103, v103, v104
	v_mul_f32_e32 v104, v10, v10
	v_mul_f32_e32 v105, v12, v12
	v_fmac_f32_e32 v104, v11, v11
	v_fmac_f32_e32 v105, v13, v13
	v_add_f32_e32 v104, v104, v105
	v_add_f32_e32 v103, v103, v104
	v_mul_f32_e32 v104, v14, v14
	v_mul_f32_e32 v105, v16, v16
	v_fmac_f32_e32 v104, v15, v15
	v_fmac_f32_e32 v105, v17, v17
	v_add_f32_e32 v104, v104, v105
	v_add_f32_e32 v103, v103, v104
	s_nop 1
	v_add_f32_dpp v103, v103, v103 quad_perm:[1,0,3,2] row_mask:0xf bank_mask:0xf
	s_nop 1
	v_add_f32_dpp v103, v103, v103 quad_perm:[2,3,0,1] row_mask:0xf bank_mask:0xf
	s_nop 1
	v_add_f32_dpp v103, v103, v103 row_half_mirror row_mask:0xf bank_mask:0xf
	s_nop 1
	v_add_f32_dpp v103, v103, v103 row_mirror row_mask:0xf bank_mask:0xf
	v_mov_b32_e32 v104, v103
	s_nop 1
	v_permlane16_swap_b32_e32 v103, v104
	s_nop 0
	v_add_f32_e32 v103, v103, v104
	v_mov_b32_e32 v104, v103
	s_nop 1
	v_permlane32_swap_b32_e32 v103, v104
	s_nop 0
	v_add_f32_e32 v103, v103, v104
	v_fma_f32 v103, v103, s37, v108
	v_rsq_f32_e32 v107, v103
	s_nop 0
	v_mul_f32_e32 v2, v2, v107
	v_mul_f32_e32 v3, v3, v107
	v_mul_f32_e32 v4, v4, v107
	v_mul_f32_e32 v5, v5, v107
	v_mul_f32_e32 v6, v6, v107
	v_mul_f32_e32 v7, v7, v107
	v_mul_f32_e32 v8, v8, v107
	v_mul_f32_e32 v9, v9, v107
	v_mul_f32_e32 v10, v10, v107
	v_mul_f32_e32 v11, v11, v107
	v_mul_f32_e32 v12, v12, v107
	v_mul_f32_e32 v13, v13, v107
	v_mul_f32_e32 v14, v14, v107
	v_mul_f32_e32 v15, v15, v107
	v_mul_f32_e32 v16, v16, v107
	v_mul_f32_e32 v17, v17, v107
	v_fma_f32 v2, v2, v66, v82
	v_fma_f32 v3, v3, v67, v83
	v_fma_f32 v4, v4, v68, v84
	v_fma_f32 v5, v5, v69, v85
	v_fma_f32 v6, v6, v70, v86
	v_fma_f32 v7, v7, v71, v87
	v_fma_f32 v8, v8, v72, v88
	v_fma_f32 v9, v9, v73, v89
	v_fma_f32 v10, v10, v74, v90
	v_fma_f32 v11, v11, v75, v91
	v_fma_f32 v12, v12, v76, v92
	v_fma_f32 v13, v13, v77, v93
	v_fma_f32 v14, v14, v78, v94
	v_fma_f32 v15, v15, v79, v95
	v_fma_f32 v16, v16, v80, v96
	v_fma_f32 v17, v17, v81, v97
	v_cvt_pk_bf16_f32 v110, v2, v3
	v_cvt_pk_bf16_f32 v111, v4, v5
	v_cvt_pk_bf16_f32 v112, v6, v7
	v_cvt_pk_bf16_f32 v113, v8, v9
	v_cvt_pk_bf16_f32 v114, v10, v11
	v_cvt_pk_bf16_f32 v115, v12, v13
	v_cvt_pk_bf16_f32 v116, v14, v15
	v_cvt_pk_bf16_f32 v117, v16, v17
	global_store_dwordx2 v101, v[110:111], s[30:31]
	global_store_dwordx2 v101, v[112:113], s[30:31] offset:512
	global_store_dwordx2 v101, v[114:115], s[30:31] offset:1024
	global_store_dwordx2 v101, v[116:117], s[30:31] offset:1536
	s_mov_b64 exec, s[0:1]
	global_store_dwordx2 v109, v[106:107], s[32:33]
	s_mov_b64 exec, -1
.Lln0_done:
.LBB0_79:
	v_readlane_b32 s4, v240, 26
	s_cmpk_gt_i32 s4, 0xef
	v_readlane_b32 s5, v240, 27
	s_cbranch_scc1 .LBB0_84
	v_readlane_b32 s4, v240, 26
	v_readlane_b32 s5, v240, 27
	s_add_i32 s4, s4, 0x8010
	s_ashr_i32 s5, s4, 31
	s_lshl_b64 s[6:7], s[4:5], 11
	s_add_u32 s6, s94, s6
	s_addc_u32 s7, s95, s7
	v_lshl_add_u64 v[2:3], v[160:161], 3, s[6:7]
	s_mov_b64 s[6:7], 0x2400000
	v_lshl_add_u64 v[2:3], v[2:3], 0, s[6:7]
	v_readlane_b32 s6, v240, 28
	v_readlane_b32 s7, v240, 29
	s_mov_b32 s16, 0
	s_mov_b32 s14, s6
	s_ashr_i32 s15, s6, 31
	v_writelane_b32 v240, s6, 28
	s_mov_b32 s17, s16
	v_mov_b32_e32 v4, 0
	v_writelane_b32 v240, s7, 29
	s_lshl_b64 s[6:7], s[14:15], 11
	s_lshl_b32 s14, s4, 1
	v_mov_b64_e32 v[6:7], s[16:17]
	v_mov_b32_e32 v5, v4
	s_branch .LBB0_82
